# S5 carry scan fully unrolled with next-batch loads prefetched under counted vmcnt; route: gain/shift/scale loads for all four quarter-rows hoisted and store-drain waits removed
# speedup vs baseline: 1.0822x; 1.0043x over previous
; __device__ __forceinline__ int opaque_tid() { int t = threadIdx.x; asm volatile("" : "+v"(t)); return t; }
; __device__ __forceinline__ u16 f2bf(float f) { unsigned r; asm("v_cvt_pk_bf16_f32 %0, %1, %1" : "=v"(r) : "v"(f)); return (u16)r; }
; #define layer launder_s(layer_)
; __device__ __forceinline__ void s5scan_item(const Params& p, int layer, int item) {
;   int tid = opaque_tid();
;   int gt = item * NT + tid;
;   int pp = gt & 63, dirsel = (gt >> 6) & 1, b = (gt >> 7) & 7, g = gt >> 10;
;   float are, aim, fre, fim;
;   s5_disc(p, layer, dirsel, g, pp, are, aim, fre, fim);
; #pragma unroll
;   for (int q = 0; q < 5; q++) { float nr = are * are - aim * aim, ni = 2.f * are * aim; are = nr; aim = ni; }
;   const float* E = (const float*)(p.ws + O_EB) + ((size_t)g * 576 + b * 72) * 256 + dirsel * 128 + pp;
;   u16* S = (u16*)(p.ws + O_UCS) + ((size_t)(g * 768 + b * 72)) * 768 + 512 + dirsel * 128 + pp;
;   float sr = 0.f, si = 0.f;
;   for (int s0 = 0; s0 < 72; s0 += 8) {
;     float er[8], ei[8];
; #pragma unroll
;     for (int k = 0; k < 8; k++) {
;       int step = s0 + k;
;       int j = dirsel == 0 ? step : (step < 8 ? 7 - step : 79 - step);
;       er[k] = E[(size_t)j * 256]; ei[k] = E[(size_t)j * 256 + 64];
;     }
; #pragma unroll
;     for (int k = 0; k < 8; k++) {
;       int step = s0 + k;
;       int j = dirsel == 0 ? step : (step < 8 ? 7 - step : 79 - step);
;       S[(size_t)j * 768] = f2bf(sr); S[(size_t)j * 768 + 64] = f2bf(si);
;       float nr = are * sr - aim * si + er[k], ni = are * si + aim * sr + ei[k];
;       sr = nr; si = ni;
;     }
;   }
.LBB0_584:
	v_mov_b32_e32 v45, 0
	v_mov_b32_e32 v47, 0
	v_mov_b32_e32 v49, 0
	v_mov_b32_e32 v51, 0
	v_mov_b32_e32 v53, 0
	v_mov_b32_e32 v55, 0
	v_mov_b32_e32 v57, 0
	v_mov_b32_e32 v59, 0
	v_mov_b32_e32 v77, 0
	v_mov_b32_e32 v79, 0
	v_mov_b32_e32 v81, 0
	v_mov_b32_e32 v83, 0
	v_mov_b32_e32 v85, 0
	v_mov_b32_e32 v87, 0
	v_mov_b32_e32 v89, 0
	v_mov_b32_e32 v91, 0
	v_mov_b32_e32 v13, 0
	v_mov_b32_e32 v44, 0
	v_cndmask_b32_e32 v44, 7, v44, vcc
	v_lshlrev_b32_e32 v10, 10, v44
	v_mov_b32_e32 v11, 0
	v_lshl_add_u64 v[10:11], v[6:7], 0, v[10:11]
	global_load_dword v60, v[10:11], off
	global_load_dword v61, v[10:11], off offset:256
	v_mov_b32_e32 v46, 1
	v_cndmask_b32_e32 v46, 6, v46, vcc
	v_lshlrev_b32_e32 v10, 10, v46
	v_mov_b32_e32 v11, 0
	v_lshl_add_u64 v[10:11], v[6:7], 0, v[10:11]
	global_load_dword v62, v[10:11], off
	global_load_dword v63, v[10:11], off offset:256
	v_mov_b32_e32 v48, 2
	v_cndmask_b32_e32 v48, 5, v48, vcc
	v_lshlrev_b32_e32 v10, 10, v48
	v_mov_b32_e32 v11, 0
	v_lshl_add_u64 v[10:11], v[6:7], 0, v[10:11]
	global_load_dword v64, v[10:11], off
	global_load_dword v65, v[10:11], off offset:256
	v_mov_b32_e32 v50, 3
	v_cndmask_b32_e32 v50, 4, v50, vcc
	v_lshlrev_b32_e32 v10, 10, v50
	v_mov_b32_e32 v11, 0
	v_lshl_add_u64 v[10:11], v[6:7], 0, v[10:11]
	global_load_dword v66, v[10:11], off
	global_load_dword v67, v[10:11], off offset:256
	v_mov_b32_e32 v52, 4
	v_cndmask_b32_e32 v52, 3, v52, vcc
	v_lshlrev_b32_e32 v10, 10, v52
	v_mov_b32_e32 v11, 0
	v_lshl_add_u64 v[10:11], v[6:7], 0, v[10:11]
	global_load_dword v68, v[10:11], off
	global_load_dword v69, v[10:11], off offset:256
	v_mov_b32_e32 v54, 5
	v_cndmask_b32_e32 v54, 2, v54, vcc
	v_lshlrev_b32_e32 v10, 10, v54
	v_mov_b32_e32 v11, 0
	v_lshl_add_u64 v[10:11], v[6:7], 0, v[10:11]
	global_load_dword v70, v[10:11], off
	global_load_dword v71, v[10:11], off offset:256
	v_mov_b32_e32 v56, 6
	v_cndmask_b32_e32 v56, 1, v56, vcc
	v_lshlrev_b32_e32 v10, 10, v56
	v_mov_b32_e32 v11, 0
	v_lshl_add_u64 v[10:11], v[6:7], 0, v[10:11]
	global_load_dword v72, v[10:11], off
	global_load_dword v73, v[10:11], off offset:256
	v_mov_b32_e32 v58, 7
	v_cndmask_b32_e32 v58, 0, v58, vcc
	v_lshlrev_b32_e32 v10, 10, v58
	v_mov_b32_e32 v11, 0
	v_lshl_add_u64 v[10:11], v[6:7], 0, v[10:11]
	global_load_dword v74, v[10:11], off
	global_load_dword v75, v[10:11], off offset:256
	v_mov_b32_e32 v76, 8
	v_mov_b32_e32 v15, 0x47
	v_cndmask_b32_e32 v76, v15, v76, vcc
	v_lshlrev_b32_e32 v10, 10, v76
	v_mov_b32_e32 v11, 0
	v_lshl_add_u64 v[10:11], v[6:7], 0, v[10:11]
	global_load_dword v92, v[10:11], off
	global_load_dword v93, v[10:11], off offset:256
	v_mov_b32_e32 v78, 9
	v_mov_b32_e32 v15, 0x46
	v_cndmask_b32_e32 v78, v15, v78, vcc
	v_lshlrev_b32_e32 v10, 10, v78
	v_mov_b32_e32 v11, 0
	v_lshl_add_u64 v[10:11], v[6:7], 0, v[10:11]
	global_load_dword v94, v[10:11], off
	global_load_dword v95, v[10:11], off offset:256
	v_mov_b32_e32 v80, 10
	v_mov_b32_e32 v15, 0x45
	v_cndmask_b32_e32 v80, v15, v80, vcc
	v_lshlrev_b32_e32 v10, 10, v80
	v_mov_b32_e32 v11, 0
	v_lshl_add_u64 v[10:11], v[6:7], 0, v[10:11]
	global_load_dword v96, v[10:11], off
	global_load_dword v97, v[10:11], off offset:256
	v_mov_b32_e32 v82, 11
	v_mov_b32_e32 v15, 0x44
	v_cndmask_b32_e32 v82, v15, v82, vcc
	v_lshlrev_b32_e32 v10, 10, v82
	v_mov_b32_e32 v11, 0
	v_lshl_add_u64 v[10:11], v[6:7], 0, v[10:11]
	global_load_dword v98, v[10:11], off
	global_load_dword v99, v[10:11], off offset:256
	v_mov_b32_e32 v84, 12
	v_mov_b32_e32 v15, 0x43
	v_cndmask_b32_e32 v84, v15, v84, vcc
	v_lshlrev_b32_e32 v10, 10, v84
	v_mov_b32_e32 v11, 0
	v_lshl_add_u64 v[10:11], v[6:7], 0, v[10:11]
	global_load_dword v100, v[10:11], off
	global_load_dword v101, v[10:11], off offset:256
	v_mov_b32_e32 v86, 13
	v_mov_b32_e32 v15, 0x42
	v_cndmask_b32_e32 v86, v15, v86, vcc
	v_lshlrev_b32_e32 v10, 10, v86
	v_mov_b32_e32 v11, 0
	v_lshl_add_u64 v[10:11], v[6:7], 0, v[10:11]
	global_load_dword v102, v[10:11], off
	global_load_dword v103, v[10:11], off offset:256
	v_mov_b32_e32 v88, 14
	v_mov_b32_e32 v15, 0x41
	v_cndmask_b32_e32 v88, v15, v88, vcc
	v_lshlrev_b32_e32 v10, 10, v88
	v_mov_b32_e32 v11, 0
	v_lshl_add_u64 v[10:11], v[6:7], 0, v[10:11]
	global_load_dword v104, v[10:11], off
	global_load_dword v105, v[10:11], off offset:256
	v_mov_b32_e32 v90, 15
	v_cndmask_b32_e32 v90, 64, v90, vcc
	v_lshlrev_b32_e32 v10, 10, v90
	v_mov_b32_e32 v11, 0
	v_lshl_add_u64 v[10:11], v[6:7], 0, v[10:11]
	global_load_dword v106, v[10:11], off
	global_load_dword v107, v[10:11], off offset:256
	v_mul_lo_u32 v12, v44, s9
	v_cvt_pk_bf16_f32 v14, v4, v4
	v_lshl_add_u64 v[16:17], v[12:13], 1, v[8:9]
	global_store_short v[16:17], v14, off
	v_cvt_pk_bf16_f32 v14, v5, v5
	global_store_short v[16:17], v14, off offset:128
	v_pk_mul_f32 v[18:19], v[2:3], v[4:5]
	s_nop 0
	v_pk_fma_f32 v[20:21], v[0:1], v[4:5], v[18:19] op_sel:[0,0,1] op_sel_hi:[1,1,0] neg_lo:[0,0,1] neg_hi:[0,0,1]
	v_pk_fma_f32 v[4:5], v[0:1], v[4:5], v[18:19] op_sel:[0,0,1] op_sel_hi:[1,1,0]
	s_nop 0
	v_mov_b32_e32 v21, v5
	s_waitcnt vmcnt(32)
	v_pk_add_f32 v[4:5], v[60:61], v[20:21]
	v_mul_lo_u32 v12, v46, s9
	v_cvt_pk_bf16_f32 v14, v4, v4
	v_lshl_add_u64 v[16:17], v[12:13], 1, v[8:9]
	global_store_short v[16:17], v14, off
	v_cvt_pk_bf16_f32 v14, v5, v5
	global_store_short v[16:17], v14, off offset:128
	v_pk_mul_f32 v[18:19], v[2:3], v[4:5]
	s_nop 0
	v_pk_fma_f32 v[20:21], v[0:1], v[4:5], v[18:19] op_sel:[0,0,1] op_sel_hi:[1,1,0] neg_lo:[0,0,1] neg_hi:[0,0,1]
	v_pk_fma_f32 v[4:5], v[0:1], v[4:5], v[18:19] op_sel:[0,0,1] op_sel_hi:[1,1,0]
	s_nop 0
	v_mov_b32_e32 v21, v5
	s_waitcnt vmcnt(32)
; __device__ __forceinline__ u16 f2bf(float f) { unsigned r; asm("v_cvt_pk_bf16_f32 %0, %1, %1" : "=v"(r) : "v"(f)); return (u16)r; }
; __device__ __forceinline__ void s5scan_item(const Params& p, int layer, int item) {
;     ...
;   for (int s0 = 0; s0 < 72; s0 += 8) {
;     float er[8], ei[8];
; #pragma unroll
;     for (int k = 0; k < 8; k++) {
;       int step = s0 + k;
;       int j = dirsel == 0 ? step : (step < 8 ? 7 - step : 79 - step);
;       er[k] = E[(size_t)j * 256]; ei[k] = E[(size_t)j * 256 + 64];
;     }
; #pragma unroll
;     for (int k = 0; k < 8; k++) {
;       int step = s0 + k;
;       int j = dirsel == 0 ? step : (step < 8 ? 7 - step : 79 - step);
;       S[(size_t)j * 768] = f2bf(sr); S[(size_t)j * 768 + 64] = f2bf(si);
;       float nr = are * sr - aim * si + er[k], ni = are * si + aim * sr + ei[k];
;       sr = nr; si = ni;
;     }
;   }
	v_pk_add_f32 v[4:5], v[62:63], v[20:21]
	v_mul_lo_u32 v12, v48, s9
	v_cvt_pk_bf16_f32 v14, v4, v4
	v_lshl_add_u64 v[16:17], v[12:13], 1, v[8:9]
	global_store_short v[16:17], v14, off
	v_cvt_pk_bf16_f32 v14, v5, v5
	global_store_short v[16:17], v14, off offset:128
	v_pk_mul_f32 v[18:19], v[2:3], v[4:5]
	s_nop 0
	v_pk_fma_f32 v[20:21], v[0:1], v[4:5], v[18:19] op_sel:[0,0,1] op_sel_hi:[1,1,0] neg_lo:[0,0,1] neg_hi:[0,0,1]
	v_pk_fma_f32 v[4:5], v[0:1], v[4:5], v[18:19] op_sel:[0,0,1] op_sel_hi:[1,1,0]
	s_nop 0
	v_mov_b32_e32 v21, v5
	s_waitcnt vmcnt(32)
	v_pk_add_f32 v[4:5], v[64:65], v[20:21]
	v_mul_lo_u32 v12, v50, s9
	v_cvt_pk_bf16_f32 v14, v4, v4
	v_lshl_add_u64 v[16:17], v[12:13], 1, v[8:9]
	global_store_short v[16:17], v14, off
	v_cvt_pk_bf16_f32 v14, v5, v5
	global_store_short v[16:17], v14, off offset:128
	v_pk_mul_f32 v[18:19], v[2:3], v[4:5]
	s_nop 0
	v_pk_fma_f32 v[20:21], v[0:1], v[4:5], v[18:19] op_sel:[0,0,1] op_sel_hi:[1,1,0] neg_lo:[0,0,1] neg_hi:[0,0,1]
	v_pk_fma_f32 v[4:5], v[0:1], v[4:5], v[18:19] op_sel:[0,0,1] op_sel_hi:[1,1,0]
	s_nop 0
	v_mov_b32_e32 v21, v5
	s_waitcnt vmcnt(32)
	v_pk_add_f32 v[4:5], v[66:67], v[20:21]
	v_mul_lo_u32 v12, v52, s9
	v_cvt_pk_bf16_f32 v14, v4, v4
	v_lshl_add_u64 v[16:17], v[12:13], 1, v[8:9]
	global_store_short v[16:17], v14, off
	v_cvt_pk_bf16_f32 v14, v5, v5
	global_store_short v[16:17], v14, off offset:128
	v_pk_mul_f32 v[18:19], v[2:3], v[4:5]
	s_nop 0
	v_pk_fma_f32 v[20:21], v[0:1], v[4:5], v[18:19] op_sel:[0,0,1] op_sel_hi:[1,1,0] neg_lo:[0,0,1] neg_hi:[0,0,1]
	v_pk_fma_f32 v[4:5], v[0:1], v[4:5], v[18:19] op_sel:[0,0,1] op_sel_hi:[1,1,0]
	s_nop 0
	v_mov_b32_e32 v21, v5
	s_waitcnt vmcnt(32)
	v_pk_add_f32 v[4:5], v[68:69], v[20:21]
	v_mul_lo_u32 v12, v54, s9
	v_cvt_pk_bf16_f32 v14, v4, v4
	v_lshl_add_u64 v[16:17], v[12:13], 1, v[8:9]
	global_store_short v[16:17], v14, off
	v_cvt_pk_bf16_f32 v14, v5, v5
	global_store_short v[16:17], v14, off offset:128
	v_pk_mul_f32 v[18:19], v[2:3], v[4:5]
	s_nop 0
	v_pk_fma_f32 v[20:21], v[0:1], v[4:5], v[18:19] op_sel:[0,0,1] op_sel_hi:[1,1,0] neg_lo:[0,0,1] neg_hi:[0,0,1]
	v_pk_fma_f32 v[4:5], v[0:1], v[4:5], v[18:19] op_sel:[0,0,1] op_sel_hi:[1,1,0]
	s_nop 0
	v_mov_b32_e32 v21, v5
	s_waitcnt vmcnt(32)
	v_pk_add_f32 v[4:5], v[70:71], v[20:21]
	v_mul_lo_u32 v12, v56, s9
	v_cvt_pk_bf16_f32 v14, v4, v4
	v_lshl_add_u64 v[16:17], v[12:13], 1, v[8:9]
	global_store_short v[16:17], v14, off
	v_cvt_pk_bf16_f32 v14, v5, v5
	global_store_short v[16:17], v14, off offset:128
	v_pk_mul_f32 v[18:19], v[2:3], v[4:5]
	s_nop 0
	v_pk_fma_f32 v[20:21], v[0:1], v[4:5], v[18:19] op_sel:[0,0,1] op_sel_hi:[1,1,0] neg_lo:[0,0,1] neg_hi:[0,0,1]
	v_pk_fma_f32 v[4:5], v[0:1], v[4:5], v[18:19] op_sel:[0,0,1] op_sel_hi:[1,1,0]
	s_nop 0
	v_mov_b32_e32 v21, v5
	s_waitcnt vmcnt(32)
	v_pk_add_f32 v[4:5], v[72:73], v[20:21]
	v_mul_lo_u32 v12, v58, s9
	v_cvt_pk_bf16_f32 v14, v4, v4
	v_lshl_add_u64 v[16:17], v[12:13], 1, v[8:9]
	global_store_short v[16:17], v14, off
	v_cvt_pk_bf16_f32 v14, v5, v5
	global_store_short v[16:17], v14, off offset:128
	v_pk_mul_f32 v[18:19], v[2:3], v[4:5]
	s_nop 0
	v_pk_fma_f32 v[20:21], v[0:1], v[4:5], v[18:19] op_sel:[0,0,1] op_sel_hi:[1,1,0] neg_lo:[0,0,1] neg_hi:[0,0,1]
	v_pk_fma_f32 v[4:5], v[0:1], v[4:5], v[18:19] op_sel:[0,0,1] op_sel_hi:[1,1,0]
	s_nop 0
	v_mov_b32_e32 v21, v5
	s_waitcnt vmcnt(32)
	v_pk_add_f32 v[4:5], v[74:75], v[20:21]
	s_waitcnt vmcnt(32)
	v_mov_b32_e32 v44, 16
	v_cndmask_b32_e32 v44, 63, v44, vcc
	v_lshlrev_b32_e32 v10, 10, v44
	v_mov_b32_e32 v11, 0
	v_lshl_add_u64 v[10:11], v[6:7], 0, v[10:11]
	global_load_dword v60, v[10:11], off
	global_load_dword v61, v[10:11], off offset:256
	v_mov_b32_e32 v46, 17
	v_cndmask_b32_e32 v46, 62, v46, vcc
	v_lshlrev_b32_e32 v10, 10, v46
	v_mov_b32_e32 v11, 0
	v_lshl_add_u64 v[10:11], v[6:7], 0, v[10:11]
	global_load_dword v62, v[10:11], off
	global_load_dword v63, v[10:11], off offset:256
	v_mov_b32_e32 v48, 18
	v_cndmask_b32_e32 v48, 61, v48, vcc
	v_lshlrev_b32_e32 v10, 10, v48
	v_mov_b32_e32 v11, 0
	v_lshl_add_u64 v[10:11], v[6:7], 0, v[10:11]
	global_load_dword v64, v[10:11], off
	global_load_dword v65, v[10:11], off offset:256
	v_mov_b32_e32 v50, 19
	v_cndmask_b32_e32 v50, 60, v50, vcc
	v_lshlrev_b32_e32 v10, 10, v50
	v_mov_b32_e32 v11, 0
	v_lshl_add_u64 v[10:11], v[6:7], 0, v[10:11]
	global_load_dword v66, v[10:11], off
	global_load_dword v67, v[10:11], off offset:256
	v_mov_b32_e32 v52, 20
	v_cndmask_b32_e32 v52, 59, v52, vcc
	v_lshlrev_b32_e32 v10, 10, v52
	v_mov_b32_e32 v11, 0
	v_lshl_add_u64 v[10:11], v[6:7], 0, v[10:11]
	global_load_dword v68, v[10:11], off
	global_load_dword v69, v[10:11], off offset:256
	v_mov_b32_e32 v54, 21
	v_cndmask_b32_e32 v54, 58, v54, vcc
	v_lshlrev_b32_e32 v10, 10, v54
	v_mov_b32_e32 v11, 0
	v_lshl_add_u64 v[10:11], v[6:7], 0, v[10:11]
	global_load_dword v70, v[10:11], off
	global_load_dword v71, v[10:11], off offset:256
	v_mov_b32_e32 v56, 22
	v_cndmask_b32_e32 v56, 57, v56, vcc
	v_lshlrev_b32_e32 v10, 10, v56
	v_mov_b32_e32 v11, 0
	v_lshl_add_u64 v[10:11], v[6:7], 0, v[10:11]
	global_load_dword v72, v[10:11], off
	global_load_dword v73, v[10:11], off offset:256
	v_mov_b32_e32 v58, 23
	v_cndmask_b32_e32 v58, 56, v58, vcc
	v_lshlrev_b32_e32 v10, 10, v58
	v_mov_b32_e32 v11, 0
	v_lshl_add_u64 v[10:11], v[6:7], 0, v[10:11]
	global_load_dword v74, v[10:11], off
	global_load_dword v75, v[10:11], off offset:256
	v_mul_lo_u32 v12, v76, s9
	v_cvt_pk_bf16_f32 v14, v4, v4
	v_lshl_add_u64 v[16:17], v[12:13], 1, v[8:9]
	global_store_short v[16:17], v14, off
	v_cvt_pk_bf16_f32 v14, v5, v5
	global_store_short v[16:17], v14, off offset:128
	v_pk_mul_f32 v[18:19], v[2:3], v[4:5]
	s_nop 0
	v_pk_fma_f32 v[20:21], v[0:1], v[4:5], v[18:19] op_sel:[0,0,1] op_sel_hi:[1,1,0] neg_lo:[0,0,1] neg_hi:[0,0,1]
	v_pk_fma_f32 v[4:5], v[0:1], v[4:5], v[18:19] op_sel:[0,0,1] op_sel_hi:[1,1,0]
	s_nop 0
	v_mov_b32_e32 v21, v5
	s_waitcnt vmcnt(48)
; __device__ __forceinline__ u16 f2bf(float f) { unsigned r; asm("v_cvt_pk_bf16_f32 %0, %1, %1" : "=v"(r) : "v"(f)); return (u16)r; }
; __device__ __forceinline__ void s5scan_item(const Params& p, int layer, int item) {
;     ...
;   for (int s0 = 0; s0 < 72; s0 += 8) {
;     float er[8], ei[8];
; #pragma unroll
;     for (int k = 0; k < 8; k++) {
;       int step = s0 + k;
;       int j = dirsel == 0 ? step : (step < 8 ? 7 - step : 79 - step);
;       er[k] = E[(size_t)j * 256]; ei[k] = E[(size_t)j * 256 + 64];
;     }
; #pragma unroll
;     for (int k = 0; k < 8; k++) {
;       int step = s0 + k;
;       int j = dirsel == 0 ? step : (step < 8 ? 7 - step : 79 - step);
;       S[(size_t)j * 768] = f2bf(sr); S[(size_t)j * 768 + 64] = f2bf(si);
;       float nr = are * sr - aim * si + er[k], ni = are * si + aim * sr + ei[k];
;       sr = nr; si = ni;
;     }
;   }
	v_pk_add_f32 v[4:5], v[92:93], v[20:21]
	v_mul_lo_u32 v12, v78, s9
	v_cvt_pk_bf16_f32 v14, v4, v4
	v_lshl_add_u64 v[16:17], v[12:13], 1, v[8:9]
	global_store_short v[16:17], v14, off
	v_cvt_pk_bf16_f32 v14, v5, v5
	global_store_short v[16:17], v14, off offset:128
	v_pk_mul_f32 v[18:19], v[2:3], v[4:5]
	s_nop 0
	v_pk_fma_f32 v[20:21], v[0:1], v[4:5], v[18:19] op_sel:[0,0,1] op_sel_hi:[1,1,0] neg_lo:[0,0,1] neg_hi:[0,0,1]
	v_pk_fma_f32 v[4:5], v[0:1], v[4:5], v[18:19] op_sel:[0,0,1] op_sel_hi:[1,1,0]
	s_nop 0
	v_mov_b32_e32 v21, v5
	s_waitcnt vmcnt(48)
	v_pk_add_f32 v[4:5], v[94:95], v[20:21]
	v_mul_lo_u32 v12, v80, s9
	v_cvt_pk_bf16_f32 v14, v4, v4
	v_lshl_add_u64 v[16:17], v[12:13], 1, v[8:9]
	global_store_short v[16:17], v14, off
	v_cvt_pk_bf16_f32 v14, v5, v5
	global_store_short v[16:17], v14, off offset:128
	v_pk_mul_f32 v[18:19], v[2:3], v[4:5]
	s_nop 0
	v_pk_fma_f32 v[20:21], v[0:1], v[4:5], v[18:19] op_sel:[0,0,1] op_sel_hi:[1,1,0] neg_lo:[0,0,1] neg_hi:[0,0,1]
	v_pk_fma_f32 v[4:5], v[0:1], v[4:5], v[18:19] op_sel:[0,0,1] op_sel_hi:[1,1,0]
	s_nop 0
	v_mov_b32_e32 v21, v5
	s_waitcnt vmcnt(48)
	v_pk_add_f32 v[4:5], v[96:97], v[20:21]
	v_mul_lo_u32 v12, v82, s9
	v_cvt_pk_bf16_f32 v14, v4, v4
	v_lshl_add_u64 v[16:17], v[12:13], 1, v[8:9]
	global_store_short v[16:17], v14, off
	v_cvt_pk_bf16_f32 v14, v5, v5
	global_store_short v[16:17], v14, off offset:128
	v_pk_mul_f32 v[18:19], v[2:3], v[4:5]
	s_nop 0
	v_pk_fma_f32 v[20:21], v[0:1], v[4:5], v[18:19] op_sel:[0,0,1] op_sel_hi:[1,1,0] neg_lo:[0,0,1] neg_hi:[0,0,1]
	v_pk_fma_f32 v[4:5], v[0:1], v[4:5], v[18:19] op_sel:[0,0,1] op_sel_hi:[1,1,0]
	s_nop 0
	v_mov_b32_e32 v21, v5
	s_waitcnt vmcnt(48)
	v_pk_add_f32 v[4:5], v[98:99], v[20:21]
	v_mul_lo_u32 v12, v84, s9
	v_cvt_pk_bf16_f32 v14, v4, v4
	v_lshl_add_u64 v[16:17], v[12:13], 1, v[8:9]
	global_store_short v[16:17], v14, off
	v_cvt_pk_bf16_f32 v14, v5, v5
	global_store_short v[16:17], v14, off offset:128
	v_pk_mul_f32 v[18:19], v[2:3], v[4:5]
	s_nop 0
	v_pk_fma_f32 v[20:21], v[0:1], v[4:5], v[18:19] op_sel:[0,0,1] op_sel_hi:[1,1,0] neg_lo:[0,0,1] neg_hi:[0,0,1]
	v_pk_fma_f32 v[4:5], v[0:1], v[4:5], v[18:19] op_sel:[0,0,1] op_sel_hi:[1,1,0]
	s_nop 0
	v_mov_b32_e32 v21, v5
	s_waitcnt vmcnt(48)
	v_pk_add_f32 v[4:5], v[100:101], v[20:21]
	v_mul_lo_u32 v12, v86, s9
	v_cvt_pk_bf16_f32 v14, v4, v4
	v_lshl_add_u64 v[16:17], v[12:13], 1, v[8:9]
	global_store_short v[16:17], v14, off
	v_cvt_pk_bf16_f32 v14, v5, v5
	global_store_short v[16:17], v14, off offset:128
	v_pk_mul_f32 v[18:19], v[2:3], v[4:5]
	s_nop 0
	v_pk_fma_f32 v[20:21], v[0:1], v[4:5], v[18:19] op_sel:[0,0,1] op_sel_hi:[1,1,0] neg_lo:[0,0,1] neg_hi:[0,0,1]
	v_pk_fma_f32 v[4:5], v[0:1], v[4:5], v[18:19] op_sel:[0,0,1] op_sel_hi:[1,1,0]
	s_nop 0
	v_mov_b32_e32 v21, v5
	s_waitcnt vmcnt(48)
	v_pk_add_f32 v[4:5], v[102:103], v[20:21]
	v_mul_lo_u32 v12, v88, s9
	v_cvt_pk_bf16_f32 v14, v4, v4
	v_lshl_add_u64 v[16:17], v[12:13], 1, v[8:9]
	global_store_short v[16:17], v14, off
	v_cvt_pk_bf16_f32 v14, v5, v5
	global_store_short v[16:17], v14, off offset:128
	v_pk_mul_f32 v[18:19], v[2:3], v[4:5]
	s_nop 0
	v_pk_fma_f32 v[20:21], v[0:1], v[4:5], v[18:19] op_sel:[0,0,1] op_sel_hi:[1,1,0] neg_lo:[0,0,1] neg_hi:[0,0,1]
	v_pk_fma_f32 v[4:5], v[0:1], v[4:5], v[18:19] op_sel:[0,0,1] op_sel_hi:[1,1,0]
	s_nop 0
	v_mov_b32_e32 v21, v5
	s_waitcnt vmcnt(48)
	v_pk_add_f32 v[4:5], v[104:105], v[20:21]
	v_mul_lo_u32 v12, v90, s9
	v_cvt_pk_bf16_f32 v14, v4, v4
	v_lshl_add_u64 v[16:17], v[12:13], 1, v[8:9]
	global_store_short v[16:17], v14, off
	v_cvt_pk_bf16_f32 v14, v5, v5
	global_store_short v[16:17], v14, off offset:128
	v_pk_mul_f32 v[18:19], v[2:3], v[4:5]
	s_nop 0
	v_pk_fma_f32 v[20:21], v[0:1], v[4:5], v[18:19] op_sel:[0,0,1] op_sel_hi:[1,1,0] neg_lo:[0,0,1] neg_hi:[0,0,1]
	v_pk_fma_f32 v[4:5], v[0:1], v[4:5], v[18:19] op_sel:[0,0,1] op_sel_hi:[1,1,0]
	s_nop 0
	v_mov_b32_e32 v21, v5
	s_waitcnt vmcnt(48)
	v_pk_add_f32 v[4:5], v[106:107], v[20:21]
	s_waitcnt vmcnt(32)
	v_mov_b32_e32 v76, 24
	v_cndmask_b32_e32 v76, 55, v76, vcc
	v_lshlrev_b32_e32 v10, 10, v76
	v_mov_b32_e32 v11, 0
	v_lshl_add_u64 v[10:11], v[6:7], 0, v[10:11]
	global_load_dword v92, v[10:11], off
	global_load_dword v93, v[10:11], off offset:256
	v_mov_b32_e32 v78, 25
	v_cndmask_b32_e32 v78, 54, v78, vcc
	v_lshlrev_b32_e32 v10, 10, v78
	v_mov_b32_e32 v11, 0
	v_lshl_add_u64 v[10:11], v[6:7], 0, v[10:11]
	global_load_dword v94, v[10:11], off
	global_load_dword v95, v[10:11], off offset:256
	v_mov_b32_e32 v80, 26
	v_cndmask_b32_e32 v80, 53, v80, vcc
	v_lshlrev_b32_e32 v10, 10, v80
	v_mov_b32_e32 v11, 0
	v_lshl_add_u64 v[10:11], v[6:7], 0, v[10:11]
	global_load_dword v96, v[10:11], off
	global_load_dword v97, v[10:11], off offset:256
	v_mov_b32_e32 v82, 27
	v_cndmask_b32_e32 v82, 52, v82, vcc
	v_lshlrev_b32_e32 v10, 10, v82
	v_mov_b32_e32 v11, 0
	v_lshl_add_u64 v[10:11], v[6:7], 0, v[10:11]
	global_load_dword v98, v[10:11], off
	global_load_dword v99, v[10:11], off offset:256
	v_mov_b32_e32 v84, 28
	v_cndmask_b32_e32 v84, 51, v84, vcc
	v_lshlrev_b32_e32 v10, 10, v84
	v_mov_b32_e32 v11, 0
	v_lshl_add_u64 v[10:11], v[6:7], 0, v[10:11]
	global_load_dword v100, v[10:11], off
	global_load_dword v101, v[10:11], off offset:256
	v_mov_b32_e32 v86, 29
	v_cndmask_b32_e32 v86, 50, v86, vcc
	v_lshlrev_b32_e32 v10, 10, v86
	v_mov_b32_e32 v11, 0
	v_lshl_add_u64 v[10:11], v[6:7], 0, v[10:11]
	global_load_dword v102, v[10:11], off
	global_load_dword v103, v[10:11], off offset:256
	v_mov_b32_e32 v88, 30
	v_cndmask_b32_e32 v88, 49, v88, vcc
	v_lshlrev_b32_e32 v10, 10, v88
	v_mov_b32_e32 v11, 0
	v_lshl_add_u64 v[10:11], v[6:7], 0, v[10:11]
	global_load_dword v104, v[10:11], off
	global_load_dword v105, v[10:11], off offset:256
	v_mov_b32_e32 v90, 31
	v_cndmask_b32_e32 v90, 48, v90, vcc
	v_lshlrev_b32_e32 v10, 10, v90
	v_mov_b32_e32 v11, 0
	v_lshl_add_u64 v[10:11], v[6:7], 0, v[10:11]
	global_load_dword v106, v[10:11], off
	global_load_dword v107, v[10:11], off offset:256
	v_mul_lo_u32 v12, v44, s9
	v_cvt_pk_bf16_f32 v14, v4, v4
	v_lshl_add_u64 v[16:17], v[12:13], 1, v[8:9]
	global_store_short v[16:17], v14, off
	v_cvt_pk_bf16_f32 v14, v5, v5
	global_store_short v[16:17], v14, off offset:128
	v_pk_mul_f32 v[18:19], v[2:3], v[4:5]
	s_nop 0
	v_pk_fma_f32 v[20:21], v[0:1], v[4:5], v[18:19] op_sel:[0,0,1] op_sel_hi:[1,1,0] neg_lo:[0,0,1] neg_hi:[0,0,1]
	v_pk_fma_f32 v[4:5], v[0:1], v[4:5], v[18:19] op_sel:[0,0,1] op_sel_hi:[1,1,0]
	s_nop 0
	v_mov_b32_e32 v21, v5
	s_waitcnt vmcnt(48)
; __device__ __forceinline__ u16 f2bf(float f) { unsigned r; asm("v_cvt_pk_bf16_f32 %0, %1, %1" : "=v"(r) : "v"(f)); return (u16)r; }
; __device__ __forceinline__ void s5scan_item(const Params& p, int layer, int item) {
;     ...
;   for (int s0 = 0; s0 < 72; s0 += 8) {
;     float er[8], ei[8];
; #pragma unroll
;     for (int k = 0; k < 8; k++) {
;       int step = s0 + k;
;       int j = dirsel == 0 ? step : (step < 8 ? 7 - step : 79 - step);
;       er[k] = E[(size_t)j * 256]; ei[k] = E[(size_t)j * 256 + 64];
;     }
; #pragma unroll
;     for (int k = 0; k < 8; k++) {
;       int step = s0 + k;
;       int j = dirsel == 0 ? step : (step < 8 ? 7 - step : 79 - step);
;       S[(size_t)j * 768] = f2bf(sr); S[(size_t)j * 768 + 64] = f2bf(si);
;       float nr = are * sr - aim * si + er[k], ni = are * si + aim * sr + ei[k];
;       sr = nr; si = ni;
;     }
;   }
	v_pk_add_f32 v[4:5], v[60:61], v[20:21]
	v_mul_lo_u32 v12, v46, s9
	v_cvt_pk_bf16_f32 v14, v4, v4
	v_lshl_add_u64 v[16:17], v[12:13], 1, v[8:9]
	global_store_short v[16:17], v14, off
	v_cvt_pk_bf16_f32 v14, v5, v5
	global_store_short v[16:17], v14, off offset:128
	v_pk_mul_f32 v[18:19], v[2:3], v[4:5]
	s_nop 0
	v_pk_fma_f32 v[20:21], v[0:1], v[4:5], v[18:19] op_sel:[0,0,1] op_sel_hi:[1,1,0] neg_lo:[0,0,1] neg_hi:[0,0,1]
	v_pk_fma_f32 v[4:5], v[0:1], v[4:5], v[18:19] op_sel:[0,0,1] op_sel_hi:[1,1,0]
	s_nop 0
	v_mov_b32_e32 v21, v5
	s_waitcnt vmcnt(48)
	v_pk_add_f32 v[4:5], v[62:63], v[20:21]
	v_mul_lo_u32 v12, v48, s9
	v_cvt_pk_bf16_f32 v14, v4, v4
	v_lshl_add_u64 v[16:17], v[12:13], 1, v[8:9]
	global_store_short v[16:17], v14, off
	v_cvt_pk_bf16_f32 v14, v5, v5
	global_store_short v[16:17], v14, off offset:128
	v_pk_mul_f32 v[18:19], v[2:3], v[4:5]
	s_nop 0
	v_pk_fma_f32 v[20:21], v[0:1], v[4:5], v[18:19] op_sel:[0,0,1] op_sel_hi:[1,1,0] neg_lo:[0,0,1] neg_hi:[0,0,1]
	v_pk_fma_f32 v[4:5], v[0:1], v[4:5], v[18:19] op_sel:[0,0,1] op_sel_hi:[1,1,0]
	s_nop 0
	v_mov_b32_e32 v21, v5
	s_waitcnt vmcnt(48)
	v_pk_add_f32 v[4:5], v[64:65], v[20:21]
	v_mul_lo_u32 v12, v50, s9
	v_cvt_pk_bf16_f32 v14, v4, v4
	v_lshl_add_u64 v[16:17], v[12:13], 1, v[8:9]
	global_store_short v[16:17], v14, off
	v_cvt_pk_bf16_f32 v14, v5, v5
	global_store_short v[16:17], v14, off offset:128
	v_pk_mul_f32 v[18:19], v[2:3], v[4:5]
	s_nop 0
	v_pk_fma_f32 v[20:21], v[0:1], v[4:5], v[18:19] op_sel:[0,0,1] op_sel_hi:[1,1,0] neg_lo:[0,0,1] neg_hi:[0,0,1]
	v_pk_fma_f32 v[4:5], v[0:1], v[4:5], v[18:19] op_sel:[0,0,1] op_sel_hi:[1,1,0]
	s_nop 0
	v_mov_b32_e32 v21, v5
	s_waitcnt vmcnt(48)
	v_pk_add_f32 v[4:5], v[66:67], v[20:21]
	v_mul_lo_u32 v12, v52, s9
	v_cvt_pk_bf16_f32 v14, v4, v4
	v_lshl_add_u64 v[16:17], v[12:13], 1, v[8:9]
	global_store_short v[16:17], v14, off
	v_cvt_pk_bf16_f32 v14, v5, v5
	global_store_short v[16:17], v14, off offset:128
	v_pk_mul_f32 v[18:19], v[2:3], v[4:5]
	s_nop 0
	v_pk_fma_f32 v[20:21], v[0:1], v[4:5], v[18:19] op_sel:[0,0,1] op_sel_hi:[1,1,0] neg_lo:[0,0,1] neg_hi:[0,0,1]
	v_pk_fma_f32 v[4:5], v[0:1], v[4:5], v[18:19] op_sel:[0,0,1] op_sel_hi:[1,1,0]
	s_nop 0
	v_mov_b32_e32 v21, v5
	s_waitcnt vmcnt(48)
	v_pk_add_f32 v[4:5], v[68:69], v[20:21]
	v_mul_lo_u32 v12, v54, s9
	v_cvt_pk_bf16_f32 v14, v4, v4
	v_lshl_add_u64 v[16:17], v[12:13], 1, v[8:9]
	global_store_short v[16:17], v14, off
	v_cvt_pk_bf16_f32 v14, v5, v5
	global_store_short v[16:17], v14, off offset:128
	v_pk_mul_f32 v[18:19], v[2:3], v[4:5]
	s_nop 0
	v_pk_fma_f32 v[20:21], v[0:1], v[4:5], v[18:19] op_sel:[0,0,1] op_sel_hi:[1,1,0] neg_lo:[0,0,1] neg_hi:[0,0,1]
	v_pk_fma_f32 v[4:5], v[0:1], v[4:5], v[18:19] op_sel:[0,0,1] op_sel_hi:[1,1,0]
	s_nop 0
	v_mov_b32_e32 v21, v5
	s_waitcnt vmcnt(48)
	v_pk_add_f32 v[4:5], v[70:71], v[20:21]
	v_mul_lo_u32 v12, v56, s9
	v_cvt_pk_bf16_f32 v14, v4, v4
	v_lshl_add_u64 v[16:17], v[12:13], 1, v[8:9]
	global_store_short v[16:17], v14, off
	v_cvt_pk_bf16_f32 v14, v5, v5
	global_store_short v[16:17], v14, off offset:128
	v_pk_mul_f32 v[18:19], v[2:3], v[4:5]
	s_nop 0
	v_pk_fma_f32 v[20:21], v[0:1], v[4:5], v[18:19] op_sel:[0,0,1] op_sel_hi:[1,1,0] neg_lo:[0,0,1] neg_hi:[0,0,1]
	v_pk_fma_f32 v[4:5], v[0:1], v[4:5], v[18:19] op_sel:[0,0,1] op_sel_hi:[1,1,0]
	s_nop 0
	v_mov_b32_e32 v21, v5
	s_waitcnt vmcnt(48)
	v_pk_add_f32 v[4:5], v[72:73], v[20:21]
	v_mul_lo_u32 v12, v58, s9
	v_cvt_pk_bf16_f32 v14, v4, v4
	v_lshl_add_u64 v[16:17], v[12:13], 1, v[8:9]
	global_store_short v[16:17], v14, off
	v_cvt_pk_bf16_f32 v14, v5, v5
	global_store_short v[16:17], v14, off offset:128
	v_pk_mul_f32 v[18:19], v[2:3], v[4:5]
	s_nop 0
	v_pk_fma_f32 v[20:21], v[0:1], v[4:5], v[18:19] op_sel:[0,0,1] op_sel_hi:[1,1,0] neg_lo:[0,0,1] neg_hi:[0,0,1]
	v_pk_fma_f32 v[4:5], v[0:1], v[4:5], v[18:19] op_sel:[0,0,1] op_sel_hi:[1,1,0]
	s_nop 0
	v_mov_b32_e32 v21, v5
	s_waitcnt vmcnt(48)
	v_pk_add_f32 v[4:5], v[74:75], v[20:21]
	s_waitcnt vmcnt(32)
	v_mov_b32_e32 v44, 32
	v_cndmask_b32_e32 v44, 47, v44, vcc
	v_lshlrev_b32_e32 v10, 10, v44
	v_mov_b32_e32 v11, 0
	v_lshl_add_u64 v[10:11], v[6:7], 0, v[10:11]
	global_load_dword v60, v[10:11], off
	global_load_dword v61, v[10:11], off offset:256
	v_mov_b32_e32 v46, 33
	v_cndmask_b32_e32 v46, 46, v46, vcc
	v_lshlrev_b32_e32 v10, 10, v46
	v_mov_b32_e32 v11, 0
	v_lshl_add_u64 v[10:11], v[6:7], 0, v[10:11]
	global_load_dword v62, v[10:11], off
	global_load_dword v63, v[10:11], off offset:256
	v_mov_b32_e32 v48, 34
	v_cndmask_b32_e32 v48, 45, v48, vcc
	v_lshlrev_b32_e32 v10, 10, v48
	v_mov_b32_e32 v11, 0
	v_lshl_add_u64 v[10:11], v[6:7], 0, v[10:11]
	global_load_dword v64, v[10:11], off
	global_load_dword v65, v[10:11], off offset:256
	v_mov_b32_e32 v50, 35
	v_cndmask_b32_e32 v50, 44, v50, vcc
	v_lshlrev_b32_e32 v10, 10, v50
	v_mov_b32_e32 v11, 0
	v_lshl_add_u64 v[10:11], v[6:7], 0, v[10:11]
	global_load_dword v66, v[10:11], off
	global_load_dword v67, v[10:11], off offset:256
	v_mov_b32_e32 v52, 36
	v_cndmask_b32_e32 v52, 43, v52, vcc
	v_lshlrev_b32_e32 v10, 10, v52
	v_mov_b32_e32 v11, 0
	v_lshl_add_u64 v[10:11], v[6:7], 0, v[10:11]
	global_load_dword v68, v[10:11], off
	global_load_dword v69, v[10:11], off offset:256
	v_mov_b32_e32 v54, 37
	v_cndmask_b32_e32 v54, 42, v54, vcc
	v_lshlrev_b32_e32 v10, 10, v54
	v_mov_b32_e32 v11, 0
	v_lshl_add_u64 v[10:11], v[6:7], 0, v[10:11]
	global_load_dword v70, v[10:11], off
	global_load_dword v71, v[10:11], off offset:256
	v_mov_b32_e32 v56, 38
	v_cndmask_b32_e32 v56, 41, v56, vcc
	v_lshlrev_b32_e32 v10, 10, v56
	v_mov_b32_e32 v11, 0
	v_lshl_add_u64 v[10:11], v[6:7], 0, v[10:11]
	global_load_dword v72, v[10:11], off
	global_load_dword v73, v[10:11], off offset:256
	v_mov_b32_e32 v58, 39
	v_cndmask_b32_e32 v58, 40, v58, vcc
	v_lshlrev_b32_e32 v10, 10, v58
	v_mov_b32_e32 v11, 0
	v_lshl_add_u64 v[10:11], v[6:7], 0, v[10:11]
	global_load_dword v74, v[10:11], off
	global_load_dword v75, v[10:11], off offset:256
	v_mul_lo_u32 v12, v76, s9
	v_cvt_pk_bf16_f32 v14, v4, v4
	v_lshl_add_u64 v[16:17], v[12:13], 1, v[8:9]
	global_store_short v[16:17], v14, off
	v_cvt_pk_bf16_f32 v14, v5, v5
	global_store_short v[16:17], v14, off offset:128
	v_pk_mul_f32 v[18:19], v[2:3], v[4:5]
	s_nop 0
	v_pk_fma_f32 v[20:21], v[0:1], v[4:5], v[18:19] op_sel:[0,0,1] op_sel_hi:[1,1,0] neg_lo:[0,0,1] neg_hi:[0,0,1]
	v_pk_fma_f32 v[4:5], v[0:1], v[4:5], v[18:19] op_sel:[0,0,1] op_sel_hi:[1,1,0]
	s_nop 0
	v_mov_b32_e32 v21, v5
	s_waitcnt vmcnt(48)
; __device__ __forceinline__ u16 f2bf(float f) { unsigned r; asm("v_cvt_pk_bf16_f32 %0, %1, %1" : "=v"(r) : "v"(f)); return (u16)r; }
; __device__ __forceinline__ void s5scan_item(const Params& p, int layer, int item) {
;     ...
;   for (int s0 = 0; s0 < 72; s0 += 8) {
;     float er[8], ei[8];
; #pragma unroll
;     for (int k = 0; k < 8; k++) {
;       int step = s0 + k;
;       int j = dirsel == 0 ? step : (step < 8 ? 7 - step : 79 - step);
;       er[k] = E[(size_t)j * 256]; ei[k] = E[(size_t)j * 256 + 64];
;     }
; #pragma unroll
;     for (int k = 0; k < 8; k++) {
;       int step = s0 + k;
;       int j = dirsel == 0 ? step : (step < 8 ? 7 - step : 79 - step);
;       S[(size_t)j * 768] = f2bf(sr); S[(size_t)j * 768 + 64] = f2bf(si);
;       float nr = are * sr - aim * si + er[k], ni = are * si + aim * sr + ei[k];
;       sr = nr; si = ni;
;     }
;   }
	v_pk_add_f32 v[4:5], v[92:93], v[20:21]
	v_mul_lo_u32 v12, v78, s9
	v_cvt_pk_bf16_f32 v14, v4, v4
	v_lshl_add_u64 v[16:17], v[12:13], 1, v[8:9]
	global_store_short v[16:17], v14, off
	v_cvt_pk_bf16_f32 v14, v5, v5
	global_store_short v[16:17], v14, off offset:128
	v_pk_mul_f32 v[18:19], v[2:3], v[4:5]
	s_nop 0
	v_pk_fma_f32 v[20:21], v[0:1], v[4:5], v[18:19] op_sel:[0,0,1] op_sel_hi:[1,1,0] neg_lo:[0,0,1] neg_hi:[0,0,1]
	v_pk_fma_f32 v[4:5], v[0:1], v[4:5], v[18:19] op_sel:[0,0,1] op_sel_hi:[1,1,0]
	s_nop 0
	v_mov_b32_e32 v21, v5
	s_waitcnt vmcnt(48)
	v_pk_add_f32 v[4:5], v[94:95], v[20:21]
	v_mul_lo_u32 v12, v80, s9
	v_cvt_pk_bf16_f32 v14, v4, v4
	v_lshl_add_u64 v[16:17], v[12:13], 1, v[8:9]
	global_store_short v[16:17], v14, off
	v_cvt_pk_bf16_f32 v14, v5, v5
	global_store_short v[16:17], v14, off offset:128
	v_pk_mul_f32 v[18:19], v[2:3], v[4:5]
	s_nop 0
	v_pk_fma_f32 v[20:21], v[0:1], v[4:5], v[18:19] op_sel:[0,0,1] op_sel_hi:[1,1,0] neg_lo:[0,0,1] neg_hi:[0,0,1]
	v_pk_fma_f32 v[4:5], v[0:1], v[4:5], v[18:19] op_sel:[0,0,1] op_sel_hi:[1,1,0]
	s_nop 0
	v_mov_b32_e32 v21, v5
	s_waitcnt vmcnt(48)
	v_pk_add_f32 v[4:5], v[96:97], v[20:21]
	v_mul_lo_u32 v12, v82, s9
	v_cvt_pk_bf16_f32 v14, v4, v4
	v_lshl_add_u64 v[16:17], v[12:13], 1, v[8:9]
	global_store_short v[16:17], v14, off
	v_cvt_pk_bf16_f32 v14, v5, v5
	global_store_short v[16:17], v14, off offset:128
	v_pk_mul_f32 v[18:19], v[2:3], v[4:5]
	s_nop 0
	v_pk_fma_f32 v[20:21], v[0:1], v[4:5], v[18:19] op_sel:[0,0,1] op_sel_hi:[1,1,0] neg_lo:[0,0,1] neg_hi:[0,0,1]
	v_pk_fma_f32 v[4:5], v[0:1], v[4:5], v[18:19] op_sel:[0,0,1] op_sel_hi:[1,1,0]
	s_nop 0
	v_mov_b32_e32 v21, v5
	s_waitcnt vmcnt(48)
	v_pk_add_f32 v[4:5], v[98:99], v[20:21]
	v_mul_lo_u32 v12, v84, s9
	v_cvt_pk_bf16_f32 v14, v4, v4
	v_lshl_add_u64 v[16:17], v[12:13], 1, v[8:9]
	global_store_short v[16:17], v14, off
	v_cvt_pk_bf16_f32 v14, v5, v5
	global_store_short v[16:17], v14, off offset:128
	v_pk_mul_f32 v[18:19], v[2:3], v[4:5]
	s_nop 0
	v_pk_fma_f32 v[20:21], v[0:1], v[4:5], v[18:19] op_sel:[0,0,1] op_sel_hi:[1,1,0] neg_lo:[0,0,1] neg_hi:[0,0,1]
	v_pk_fma_f32 v[4:5], v[0:1], v[4:5], v[18:19] op_sel:[0,0,1] op_sel_hi:[1,1,0]
	s_nop 0
	v_mov_b32_e32 v21, v5
	s_waitcnt vmcnt(48)
	v_pk_add_f32 v[4:5], v[100:101], v[20:21]
	v_mul_lo_u32 v12, v86, s9
	v_cvt_pk_bf16_f32 v14, v4, v4
	v_lshl_add_u64 v[16:17], v[12:13], 1, v[8:9]
	global_store_short v[16:17], v14, off
	v_cvt_pk_bf16_f32 v14, v5, v5
	global_store_short v[16:17], v14, off offset:128
	v_pk_mul_f32 v[18:19], v[2:3], v[4:5]
	s_nop 0
	v_pk_fma_f32 v[20:21], v[0:1], v[4:5], v[18:19] op_sel:[0,0,1] op_sel_hi:[1,1,0] neg_lo:[0,0,1] neg_hi:[0,0,1]
	v_pk_fma_f32 v[4:5], v[0:1], v[4:5], v[18:19] op_sel:[0,0,1] op_sel_hi:[1,1,0]
	s_nop 0
	v_mov_b32_e32 v21, v5
	s_waitcnt vmcnt(48)
	v_pk_add_f32 v[4:5], v[102:103], v[20:21]
	v_mul_lo_u32 v12, v88, s9
	v_cvt_pk_bf16_f32 v14, v4, v4
	v_lshl_add_u64 v[16:17], v[12:13], 1, v[8:9]
	global_store_short v[16:17], v14, off
	v_cvt_pk_bf16_f32 v14, v5, v5
	global_store_short v[16:17], v14, off offset:128
	v_pk_mul_f32 v[18:19], v[2:3], v[4:5]
	s_nop 0
	v_pk_fma_f32 v[20:21], v[0:1], v[4:5], v[18:19] op_sel:[0,0,1] op_sel_hi:[1,1,0] neg_lo:[0,0,1] neg_hi:[0,0,1]
	v_pk_fma_f32 v[4:5], v[0:1], v[4:5], v[18:19] op_sel:[0,0,1] op_sel_hi:[1,1,0]
	s_nop 0
	v_mov_b32_e32 v21, v5
	s_waitcnt vmcnt(48)
	v_pk_add_f32 v[4:5], v[104:105], v[20:21]
	v_mul_lo_u32 v12, v90, s9
	v_cvt_pk_bf16_f32 v14, v4, v4
	v_lshl_add_u64 v[16:17], v[12:13], 1, v[8:9]
	global_store_short v[16:17], v14, off
	v_cvt_pk_bf16_f32 v14, v5, v5
	global_store_short v[16:17], v14, off offset:128
	v_pk_mul_f32 v[18:19], v[2:3], v[4:5]
	s_nop 0
	v_pk_fma_f32 v[20:21], v[0:1], v[4:5], v[18:19] op_sel:[0,0,1] op_sel_hi:[1,1,0] neg_lo:[0,0,1] neg_hi:[0,0,1]
	v_pk_fma_f32 v[4:5], v[0:1], v[4:5], v[18:19] op_sel:[0,0,1] op_sel_hi:[1,1,0]
	s_nop 0
	v_mov_b32_e32 v21, v5
	s_waitcnt vmcnt(48)
	v_pk_add_f32 v[4:5], v[106:107], v[20:21]
	s_waitcnt vmcnt(32)
	v_mov_b32_e32 v76, 40
	v_cndmask_b32_e32 v76, 39, v76, vcc
	v_lshlrev_b32_e32 v10, 10, v76
	v_mov_b32_e32 v11, 0
	v_lshl_add_u64 v[10:11], v[6:7], 0, v[10:11]
	global_load_dword v92, v[10:11], off
	global_load_dword v93, v[10:11], off offset:256
	v_mov_b32_e32 v78, 41
	v_cndmask_b32_e32 v78, 38, v78, vcc
	v_lshlrev_b32_e32 v10, 10, v78
	v_mov_b32_e32 v11, 0
	v_lshl_add_u64 v[10:11], v[6:7], 0, v[10:11]
	global_load_dword v94, v[10:11], off
	global_load_dword v95, v[10:11], off offset:256
	v_mov_b32_e32 v80, 42
	v_cndmask_b32_e32 v80, 37, v80, vcc
	v_lshlrev_b32_e32 v10, 10, v80
	v_mov_b32_e32 v11, 0
	v_lshl_add_u64 v[10:11], v[6:7], 0, v[10:11]
	global_load_dword v96, v[10:11], off
	global_load_dword v97, v[10:11], off offset:256
	v_mov_b32_e32 v82, 43
	v_cndmask_b32_e32 v82, 36, v82, vcc
	v_lshlrev_b32_e32 v10, 10, v82
	v_mov_b32_e32 v11, 0
	v_lshl_add_u64 v[10:11], v[6:7], 0, v[10:11]
	global_load_dword v98, v[10:11], off
	global_load_dword v99, v[10:11], off offset:256
	v_mov_b32_e32 v84, 44
	v_cndmask_b32_e32 v84, 35, v84, vcc
	v_lshlrev_b32_e32 v10, 10, v84
	v_mov_b32_e32 v11, 0
	v_lshl_add_u64 v[10:11], v[6:7], 0, v[10:11]
	global_load_dword v100, v[10:11], off
	global_load_dword v101, v[10:11], off offset:256
	v_mov_b32_e32 v86, 45
	v_cndmask_b32_e32 v86, 34, v86, vcc
	v_lshlrev_b32_e32 v10, 10, v86
	v_mov_b32_e32 v11, 0
	v_lshl_add_u64 v[10:11], v[6:7], 0, v[10:11]
	global_load_dword v102, v[10:11], off
	global_load_dword v103, v[10:11], off offset:256
	v_mov_b32_e32 v88, 46
	v_cndmask_b32_e32 v88, 33, v88, vcc
	v_lshlrev_b32_e32 v10, 10, v88
	v_mov_b32_e32 v11, 0
	v_lshl_add_u64 v[10:11], v[6:7], 0, v[10:11]
	global_load_dword v104, v[10:11], off
	global_load_dword v105, v[10:11], off offset:256
	v_mov_b32_e32 v90, 47
	v_cndmask_b32_e32 v90, 32, v90, vcc
	v_lshlrev_b32_e32 v10, 10, v90
	v_mov_b32_e32 v11, 0
	v_lshl_add_u64 v[10:11], v[6:7], 0, v[10:11]
	global_load_dword v106, v[10:11], off
	global_load_dword v107, v[10:11], off offset:256
	v_mul_lo_u32 v12, v44, s9
	v_cvt_pk_bf16_f32 v14, v4, v4
	v_lshl_add_u64 v[16:17], v[12:13], 1, v[8:9]
	global_store_short v[16:17], v14, off
	v_cvt_pk_bf16_f32 v14, v5, v5
	global_store_short v[16:17], v14, off offset:128
	v_pk_mul_f32 v[18:19], v[2:3], v[4:5]
	s_nop 0
	v_pk_fma_f32 v[20:21], v[0:1], v[4:5], v[18:19] op_sel:[0,0,1] op_sel_hi:[1,1,0] neg_lo:[0,0,1] neg_hi:[0,0,1]
	v_pk_fma_f32 v[4:5], v[0:1], v[4:5], v[18:19] op_sel:[0,0,1] op_sel_hi:[1,1,0]
	s_nop 0
	v_mov_b32_e32 v21, v5
	s_waitcnt vmcnt(48)
; __device__ __forceinline__ u16 f2bf(float f) { unsigned r; asm("v_cvt_pk_bf16_f32 %0, %1, %1" : "=v"(r) : "v"(f)); return (u16)r; }
; __device__ __forceinline__ void s5scan_item(const Params& p, int layer, int item) {
;     ...
;   for (int s0 = 0; s0 < 72; s0 += 8) {
;     float er[8], ei[8];
; #pragma unroll
;     for (int k = 0; k < 8; k++) {
;       int step = s0 + k;
;       int j = dirsel == 0 ? step : (step < 8 ? 7 - step : 79 - step);
;       er[k] = E[(size_t)j * 256]; ei[k] = E[(size_t)j * 256 + 64];
;     }
; #pragma unroll
;     for (int k = 0; k < 8; k++) {
;       int step = s0 + k;
;       int j = dirsel == 0 ? step : (step < 8 ? 7 - step : 79 - step);
;       S[(size_t)j * 768] = f2bf(sr); S[(size_t)j * 768 + 64] = f2bf(si);
;       float nr = are * sr - aim * si + er[k], ni = are * si + aim * sr + ei[k];
;       sr = nr; si = ni;
;     }
;   }
	v_pk_add_f32 v[4:5], v[60:61], v[20:21]
	v_mul_lo_u32 v12, v46, s9
	v_cvt_pk_bf16_f32 v14, v4, v4
	v_lshl_add_u64 v[16:17], v[12:13], 1, v[8:9]
	global_store_short v[16:17], v14, off
	v_cvt_pk_bf16_f32 v14, v5, v5
	global_store_short v[16:17], v14, off offset:128
	v_pk_mul_f32 v[18:19], v[2:3], v[4:5]
	s_nop 0
	v_pk_fma_f32 v[20:21], v[0:1], v[4:5], v[18:19] op_sel:[0,0,1] op_sel_hi:[1,1,0] neg_lo:[0,0,1] neg_hi:[0,0,1]
	v_pk_fma_f32 v[4:5], v[0:1], v[4:5], v[18:19] op_sel:[0,0,1] op_sel_hi:[1,1,0]
	s_nop 0
	v_mov_b32_e32 v21, v5
	s_waitcnt vmcnt(48)
	v_pk_add_f32 v[4:5], v[62:63], v[20:21]
	v_mul_lo_u32 v12, v48, s9
	v_cvt_pk_bf16_f32 v14, v4, v4
	v_lshl_add_u64 v[16:17], v[12:13], 1, v[8:9]
	global_store_short v[16:17], v14, off
	v_cvt_pk_bf16_f32 v14, v5, v5
	global_store_short v[16:17], v14, off offset:128
	v_pk_mul_f32 v[18:19], v[2:3], v[4:5]
	s_nop 0
	v_pk_fma_f32 v[20:21], v[0:1], v[4:5], v[18:19] op_sel:[0,0,1] op_sel_hi:[1,1,0] neg_lo:[0,0,1] neg_hi:[0,0,1]
	v_pk_fma_f32 v[4:5], v[0:1], v[4:5], v[18:19] op_sel:[0,0,1] op_sel_hi:[1,1,0]
	s_nop 0
	v_mov_b32_e32 v21, v5
	s_waitcnt vmcnt(48)
	v_pk_add_f32 v[4:5], v[64:65], v[20:21]
	v_mul_lo_u32 v12, v50, s9
	v_cvt_pk_bf16_f32 v14, v4, v4
	v_lshl_add_u64 v[16:17], v[12:13], 1, v[8:9]
	global_store_short v[16:17], v14, off
	v_cvt_pk_bf16_f32 v14, v5, v5
	global_store_short v[16:17], v14, off offset:128
	v_pk_mul_f32 v[18:19], v[2:3], v[4:5]
	s_nop 0
	v_pk_fma_f32 v[20:21], v[0:1], v[4:5], v[18:19] op_sel:[0,0,1] op_sel_hi:[1,1,0] neg_lo:[0,0,1] neg_hi:[0,0,1]
	v_pk_fma_f32 v[4:5], v[0:1], v[4:5], v[18:19] op_sel:[0,0,1] op_sel_hi:[1,1,0]
	s_nop 0
	v_mov_b32_e32 v21, v5
	s_waitcnt vmcnt(48)
	v_pk_add_f32 v[4:5], v[66:67], v[20:21]
	v_mul_lo_u32 v12, v52, s9
	v_cvt_pk_bf16_f32 v14, v4, v4
	v_lshl_add_u64 v[16:17], v[12:13], 1, v[8:9]
	global_store_short v[16:17], v14, off
	v_cvt_pk_bf16_f32 v14, v5, v5
	global_store_short v[16:17], v14, off offset:128
	v_pk_mul_f32 v[18:19], v[2:3], v[4:5]
	s_nop 0
	v_pk_fma_f32 v[20:21], v[0:1], v[4:5], v[18:19] op_sel:[0,0,1] op_sel_hi:[1,1,0] neg_lo:[0,0,1] neg_hi:[0,0,1]
	v_pk_fma_f32 v[4:5], v[0:1], v[4:5], v[18:19] op_sel:[0,0,1] op_sel_hi:[1,1,0]
	s_nop 0
	v_mov_b32_e32 v21, v5
	s_waitcnt vmcnt(48)
	v_pk_add_f32 v[4:5], v[68:69], v[20:21]
	v_mul_lo_u32 v12, v54, s9
	v_cvt_pk_bf16_f32 v14, v4, v4
	v_lshl_add_u64 v[16:17], v[12:13], 1, v[8:9]
	global_store_short v[16:17], v14, off
	v_cvt_pk_bf16_f32 v14, v5, v5
	global_store_short v[16:17], v14, off offset:128
	v_pk_mul_f32 v[18:19], v[2:3], v[4:5]
	s_nop 0
	v_pk_fma_f32 v[20:21], v[0:1], v[4:5], v[18:19] op_sel:[0,0,1] op_sel_hi:[1,1,0] neg_lo:[0,0,1] neg_hi:[0,0,1]
	v_pk_fma_f32 v[4:5], v[0:1], v[4:5], v[18:19] op_sel:[0,0,1] op_sel_hi:[1,1,0]
	s_nop 0
	v_mov_b32_e32 v21, v5
	s_waitcnt vmcnt(48)
	v_pk_add_f32 v[4:5], v[70:71], v[20:21]
	v_mul_lo_u32 v12, v56, s9
	v_cvt_pk_bf16_f32 v14, v4, v4
	v_lshl_add_u64 v[16:17], v[12:13], 1, v[8:9]
	global_store_short v[16:17], v14, off
	v_cvt_pk_bf16_f32 v14, v5, v5
	global_store_short v[16:17], v14, off offset:128
	v_pk_mul_f32 v[18:19], v[2:3], v[4:5]
	s_nop 0
	v_pk_fma_f32 v[20:21], v[0:1], v[4:5], v[18:19] op_sel:[0,0,1] op_sel_hi:[1,1,0] neg_lo:[0,0,1] neg_hi:[0,0,1]
	v_pk_fma_f32 v[4:5], v[0:1], v[4:5], v[18:19] op_sel:[0,0,1] op_sel_hi:[1,1,0]
	s_nop 0
	v_mov_b32_e32 v21, v5
	s_waitcnt vmcnt(48)
	v_pk_add_f32 v[4:5], v[72:73], v[20:21]
	v_mul_lo_u32 v12, v58, s9
	v_cvt_pk_bf16_f32 v14, v4, v4
	v_lshl_add_u64 v[16:17], v[12:13], 1, v[8:9]
	global_store_short v[16:17], v14, off
	v_cvt_pk_bf16_f32 v14, v5, v5
	global_store_short v[16:17], v14, off offset:128
	v_pk_mul_f32 v[18:19], v[2:3], v[4:5]
	s_nop 0
	v_pk_fma_f32 v[20:21], v[0:1], v[4:5], v[18:19] op_sel:[0,0,1] op_sel_hi:[1,1,0] neg_lo:[0,0,1] neg_hi:[0,0,1]
	v_pk_fma_f32 v[4:5], v[0:1], v[4:5], v[18:19] op_sel:[0,0,1] op_sel_hi:[1,1,0]
	s_nop 0
	v_mov_b32_e32 v21, v5
	s_waitcnt vmcnt(48)
	v_pk_add_f32 v[4:5], v[74:75], v[20:21]
	s_waitcnt vmcnt(32)
	v_mov_b32_e32 v44, 48
	v_cndmask_b32_e32 v44, 31, v44, vcc
	v_lshlrev_b32_e32 v10, 10, v44
	v_mov_b32_e32 v11, 0
	v_lshl_add_u64 v[10:11], v[6:7], 0, v[10:11]
	global_load_dword v60, v[10:11], off
	global_load_dword v61, v[10:11], off offset:256
	v_mov_b32_e32 v46, 49
	v_cndmask_b32_e32 v46, 30, v46, vcc
	v_lshlrev_b32_e32 v10, 10, v46
	v_mov_b32_e32 v11, 0
	v_lshl_add_u64 v[10:11], v[6:7], 0, v[10:11]
	global_load_dword v62, v[10:11], off
	global_load_dword v63, v[10:11], off offset:256
	v_mov_b32_e32 v48, 50
	v_cndmask_b32_e32 v48, 29, v48, vcc
	v_lshlrev_b32_e32 v10, 10, v48
	v_mov_b32_e32 v11, 0
	v_lshl_add_u64 v[10:11], v[6:7], 0, v[10:11]
	global_load_dword v64, v[10:11], off
	global_load_dword v65, v[10:11], off offset:256
	v_mov_b32_e32 v50, 51
	v_cndmask_b32_e32 v50, 28, v50, vcc
	v_lshlrev_b32_e32 v10, 10, v50
	v_mov_b32_e32 v11, 0
	v_lshl_add_u64 v[10:11], v[6:7], 0, v[10:11]
	global_load_dword v66, v[10:11], off
	global_load_dword v67, v[10:11], off offset:256
	v_mov_b32_e32 v52, 52
	v_cndmask_b32_e32 v52, 27, v52, vcc
	v_lshlrev_b32_e32 v10, 10, v52
	v_mov_b32_e32 v11, 0
	v_lshl_add_u64 v[10:11], v[6:7], 0, v[10:11]
	global_load_dword v68, v[10:11], off
	global_load_dword v69, v[10:11], off offset:256
	v_mov_b32_e32 v54, 53
	v_cndmask_b32_e32 v54, 26, v54, vcc
	v_lshlrev_b32_e32 v10, 10, v54
	v_mov_b32_e32 v11, 0
	v_lshl_add_u64 v[10:11], v[6:7], 0, v[10:11]
	global_load_dword v70, v[10:11], off
	global_load_dword v71, v[10:11], off offset:256
	v_mov_b32_e32 v56, 54
	v_cndmask_b32_e32 v56, 25, v56, vcc
	v_lshlrev_b32_e32 v10, 10, v56
	v_mov_b32_e32 v11, 0
	v_lshl_add_u64 v[10:11], v[6:7], 0, v[10:11]
	global_load_dword v72, v[10:11], off
	global_load_dword v73, v[10:11], off offset:256
	v_mov_b32_e32 v58, 55
	v_cndmask_b32_e32 v58, 24, v58, vcc
	v_lshlrev_b32_e32 v10, 10, v58
	v_mov_b32_e32 v11, 0
	v_lshl_add_u64 v[10:11], v[6:7], 0, v[10:11]
	global_load_dword v74, v[10:11], off
	global_load_dword v75, v[10:11], off offset:256
	v_mul_lo_u32 v12, v76, s9
	v_cvt_pk_bf16_f32 v14, v4, v4
	v_lshl_add_u64 v[16:17], v[12:13], 1, v[8:9]
	global_store_short v[16:17], v14, off
	v_cvt_pk_bf16_f32 v14, v5, v5
	global_store_short v[16:17], v14, off offset:128
	v_pk_mul_f32 v[18:19], v[2:3], v[4:5]
	s_nop 0
	v_pk_fma_f32 v[20:21], v[0:1], v[4:5], v[18:19] op_sel:[0,0,1] op_sel_hi:[1,1,0] neg_lo:[0,0,1] neg_hi:[0,0,1]
	v_pk_fma_f32 v[4:5], v[0:1], v[4:5], v[18:19] op_sel:[0,0,1] op_sel_hi:[1,1,0]
	s_nop 0
	v_mov_b32_e32 v21, v5
	s_waitcnt vmcnt(48)
; __device__ __forceinline__ u16 f2bf(float f) { unsigned r; asm("v_cvt_pk_bf16_f32 %0, %1, %1" : "=v"(r) : "v"(f)); return (u16)r; }
; __device__ __forceinline__ void s5scan_item(const Params& p, int layer, int item) {
;     ...
;   for (int s0 = 0; s0 < 72; s0 += 8) {
;     float er[8], ei[8];
; #pragma unroll
;     for (int k = 0; k < 8; k++) {
;       int step = s0 + k;
;       int j = dirsel == 0 ? step : (step < 8 ? 7 - step : 79 - step);
;       er[k] = E[(size_t)j * 256]; ei[k] = E[(size_t)j * 256 + 64];
;     }
; #pragma unroll
;     for (int k = 0; k < 8; k++) {
;       int step = s0 + k;
;       int j = dirsel == 0 ? step : (step < 8 ? 7 - step : 79 - step);
;       S[(size_t)j * 768] = f2bf(sr); S[(size_t)j * 768 + 64] = f2bf(si);
;       float nr = are * sr - aim * si + er[k], ni = are * si + aim * sr + ei[k];
;       sr = nr; si = ni;
;     }
;   }
	v_pk_add_f32 v[4:5], v[92:93], v[20:21]
	v_mul_lo_u32 v12, v78, s9
	v_cvt_pk_bf16_f32 v14, v4, v4
	v_lshl_add_u64 v[16:17], v[12:13], 1, v[8:9]
	global_store_short v[16:17], v14, off
	v_cvt_pk_bf16_f32 v14, v5, v5
	global_store_short v[16:17], v14, off offset:128
	v_pk_mul_f32 v[18:19], v[2:3], v[4:5]
	s_nop 0
	v_pk_fma_f32 v[20:21], v[0:1], v[4:5], v[18:19] op_sel:[0,0,1] op_sel_hi:[1,1,0] neg_lo:[0,0,1] neg_hi:[0,0,1]
	v_pk_fma_f32 v[4:5], v[0:1], v[4:5], v[18:19] op_sel:[0,0,1] op_sel_hi:[1,1,0]
	s_nop 0
	v_mov_b32_e32 v21, v5
	s_waitcnt vmcnt(48)
	v_pk_add_f32 v[4:5], v[94:95], v[20:21]
	v_mul_lo_u32 v12, v80, s9
	v_cvt_pk_bf16_f32 v14, v4, v4
	v_lshl_add_u64 v[16:17], v[12:13], 1, v[8:9]
	global_store_short v[16:17], v14, off
	v_cvt_pk_bf16_f32 v14, v5, v5
	global_store_short v[16:17], v14, off offset:128
	v_pk_mul_f32 v[18:19], v[2:3], v[4:5]
	s_nop 0
	v_pk_fma_f32 v[20:21], v[0:1], v[4:5], v[18:19] op_sel:[0,0,1] op_sel_hi:[1,1,0] neg_lo:[0,0,1] neg_hi:[0,0,1]
	v_pk_fma_f32 v[4:5], v[0:1], v[4:5], v[18:19] op_sel:[0,0,1] op_sel_hi:[1,1,0]
	s_nop 0
	v_mov_b32_e32 v21, v5
	s_waitcnt vmcnt(48)
	v_pk_add_f32 v[4:5], v[96:97], v[20:21]
	v_mul_lo_u32 v12, v82, s9
	v_cvt_pk_bf16_f32 v14, v4, v4
	v_lshl_add_u64 v[16:17], v[12:13], 1, v[8:9]
	global_store_short v[16:17], v14, off
	v_cvt_pk_bf16_f32 v14, v5, v5
	global_store_short v[16:17], v14, off offset:128
	v_pk_mul_f32 v[18:19], v[2:3], v[4:5]
	s_nop 0
	v_pk_fma_f32 v[20:21], v[0:1], v[4:5], v[18:19] op_sel:[0,0,1] op_sel_hi:[1,1,0] neg_lo:[0,0,1] neg_hi:[0,0,1]
	v_pk_fma_f32 v[4:5], v[0:1], v[4:5], v[18:19] op_sel:[0,0,1] op_sel_hi:[1,1,0]
	s_nop 0
	v_mov_b32_e32 v21, v5
	s_waitcnt vmcnt(48)
	v_pk_add_f32 v[4:5], v[98:99], v[20:21]
	v_mul_lo_u32 v12, v84, s9
	v_cvt_pk_bf16_f32 v14, v4, v4
	v_lshl_add_u64 v[16:17], v[12:13], 1, v[8:9]
	global_store_short v[16:17], v14, off
	v_cvt_pk_bf16_f32 v14, v5, v5
	global_store_short v[16:17], v14, off offset:128
	v_pk_mul_f32 v[18:19], v[2:3], v[4:5]
	s_nop 0
	v_pk_fma_f32 v[20:21], v[0:1], v[4:5], v[18:19] op_sel:[0,0,1] op_sel_hi:[1,1,0] neg_lo:[0,0,1] neg_hi:[0,0,1]
	v_pk_fma_f32 v[4:5], v[0:1], v[4:5], v[18:19] op_sel:[0,0,1] op_sel_hi:[1,1,0]
	s_nop 0
	v_mov_b32_e32 v21, v5
	s_waitcnt vmcnt(48)
	v_pk_add_f32 v[4:5], v[100:101], v[20:21]
	v_mul_lo_u32 v12, v86, s9
	v_cvt_pk_bf16_f32 v14, v4, v4
	v_lshl_add_u64 v[16:17], v[12:13], 1, v[8:9]
	global_store_short v[16:17], v14, off
	v_cvt_pk_bf16_f32 v14, v5, v5
	global_store_short v[16:17], v14, off offset:128
	v_pk_mul_f32 v[18:19], v[2:3], v[4:5]
	s_nop 0
	v_pk_fma_f32 v[20:21], v[0:1], v[4:5], v[18:19] op_sel:[0,0,1] op_sel_hi:[1,1,0] neg_lo:[0,0,1] neg_hi:[0,0,1]
	v_pk_fma_f32 v[4:5], v[0:1], v[4:5], v[18:19] op_sel:[0,0,1] op_sel_hi:[1,1,0]
	s_nop 0
	v_mov_b32_e32 v21, v5
	s_waitcnt vmcnt(48)
	v_pk_add_f32 v[4:5], v[102:103], v[20:21]
	v_mul_lo_u32 v12, v88, s9
	v_cvt_pk_bf16_f32 v14, v4, v4
	v_lshl_add_u64 v[16:17], v[12:13], 1, v[8:9]
	global_store_short v[16:17], v14, off
	v_cvt_pk_bf16_f32 v14, v5, v5
	global_store_short v[16:17], v14, off offset:128
	v_pk_mul_f32 v[18:19], v[2:3], v[4:5]
	s_nop 0
	v_pk_fma_f32 v[20:21], v[0:1], v[4:5], v[18:19] op_sel:[0,0,1] op_sel_hi:[1,1,0] neg_lo:[0,0,1] neg_hi:[0,0,1]
	v_pk_fma_f32 v[4:5], v[0:1], v[4:5], v[18:19] op_sel:[0,0,1] op_sel_hi:[1,1,0]
	s_nop 0
	v_mov_b32_e32 v21, v5
	s_waitcnt vmcnt(48)
	v_pk_add_f32 v[4:5], v[104:105], v[20:21]
	v_mul_lo_u32 v12, v90, s9
	v_cvt_pk_bf16_f32 v14, v4, v4
	v_lshl_add_u64 v[16:17], v[12:13], 1, v[8:9]
	global_store_short v[16:17], v14, off
	v_cvt_pk_bf16_f32 v14, v5, v5
	global_store_short v[16:17], v14, off offset:128
	v_pk_mul_f32 v[18:19], v[2:3], v[4:5]
	s_nop 0
	v_pk_fma_f32 v[20:21], v[0:1], v[4:5], v[18:19] op_sel:[0,0,1] op_sel_hi:[1,1,0] neg_lo:[0,0,1] neg_hi:[0,0,1]
	v_pk_fma_f32 v[4:5], v[0:1], v[4:5], v[18:19] op_sel:[0,0,1] op_sel_hi:[1,1,0]
	s_nop 0
	v_mov_b32_e32 v21, v5
	s_waitcnt vmcnt(48)
	v_pk_add_f32 v[4:5], v[106:107], v[20:21]
	s_waitcnt vmcnt(32)
	v_mov_b32_e32 v76, 56
	v_cndmask_b32_e32 v76, 23, v76, vcc
	v_lshlrev_b32_e32 v10, 10, v76
	v_mov_b32_e32 v11, 0
	v_lshl_add_u64 v[10:11], v[6:7], 0, v[10:11]
	global_load_dword v92, v[10:11], off
	global_load_dword v93, v[10:11], off offset:256
	v_mov_b32_e32 v78, 57
	v_cndmask_b32_e32 v78, 22, v78, vcc
	v_lshlrev_b32_e32 v10, 10, v78
	v_mov_b32_e32 v11, 0
	v_lshl_add_u64 v[10:11], v[6:7], 0, v[10:11]
	global_load_dword v94, v[10:11], off
	global_load_dword v95, v[10:11], off offset:256
	v_mov_b32_e32 v80, 58
	v_cndmask_b32_e32 v80, 21, v80, vcc
	v_lshlrev_b32_e32 v10, 10, v80
	v_mov_b32_e32 v11, 0
	v_lshl_add_u64 v[10:11], v[6:7], 0, v[10:11]
	global_load_dword v96, v[10:11], off
	global_load_dword v97, v[10:11], off offset:256
	v_mov_b32_e32 v82, 59
	v_cndmask_b32_e32 v82, 20, v82, vcc
	v_lshlrev_b32_e32 v10, 10, v82
	v_mov_b32_e32 v11, 0
	v_lshl_add_u64 v[10:11], v[6:7], 0, v[10:11]
	global_load_dword v98, v[10:11], off
	global_load_dword v99, v[10:11], off offset:256
	v_mov_b32_e32 v84, 60
	v_cndmask_b32_e32 v84, 19, v84, vcc
	v_lshlrev_b32_e32 v10, 10, v84
	v_mov_b32_e32 v11, 0
	v_lshl_add_u64 v[10:11], v[6:7], 0, v[10:11]
	global_load_dword v100, v[10:11], off
	global_load_dword v101, v[10:11], off offset:256
	v_mov_b32_e32 v86, 61
	v_cndmask_b32_e32 v86, 18, v86, vcc
	v_lshlrev_b32_e32 v10, 10, v86
	v_mov_b32_e32 v11, 0
	v_lshl_add_u64 v[10:11], v[6:7], 0, v[10:11]
	global_load_dword v102, v[10:11], off
	global_load_dword v103, v[10:11], off offset:256
	v_mov_b32_e32 v88, 62
	v_cndmask_b32_e32 v88, 17, v88, vcc
	v_lshlrev_b32_e32 v10, 10, v88
	v_mov_b32_e32 v11, 0
	v_lshl_add_u64 v[10:11], v[6:7], 0, v[10:11]
	global_load_dword v104, v[10:11], off
	global_load_dword v105, v[10:11], off offset:256
	v_mov_b32_e32 v90, 63
	v_cndmask_b32_e32 v90, 16, v90, vcc
	v_lshlrev_b32_e32 v10, 10, v90
	v_mov_b32_e32 v11, 0
	v_lshl_add_u64 v[10:11], v[6:7], 0, v[10:11]
	global_load_dword v106, v[10:11], off
	global_load_dword v107, v[10:11], off offset:256
	v_mul_lo_u32 v12, v44, s9
	v_cvt_pk_bf16_f32 v14, v4, v4
	v_lshl_add_u64 v[16:17], v[12:13], 1, v[8:9]
	global_store_short v[16:17], v14, off
	v_cvt_pk_bf16_f32 v14, v5, v5
	global_store_short v[16:17], v14, off offset:128
	v_pk_mul_f32 v[18:19], v[2:3], v[4:5]
	s_nop 0
	v_pk_fma_f32 v[20:21], v[0:1], v[4:5], v[18:19] op_sel:[0,0,1] op_sel_hi:[1,1,0] neg_lo:[0,0,1] neg_hi:[0,0,1]
	v_pk_fma_f32 v[4:5], v[0:1], v[4:5], v[18:19] op_sel:[0,0,1] op_sel_hi:[1,1,0]
	s_nop 0
	v_mov_b32_e32 v21, v5
	s_waitcnt vmcnt(48)
; __device__ __forceinline__ u16 f2bf(float f) { unsigned r; asm("v_cvt_pk_bf16_f32 %0, %1, %1" : "=v"(r) : "v"(f)); return (u16)r; }
; __device__ __forceinline__ void s5scan_item(const Params& p, int layer, int item) {
;     ...
;   for (int s0 = 0; s0 < 72; s0 += 8) {
;     float er[8], ei[8];
; #pragma unroll
;     for (int k = 0; k < 8; k++) {
;       int step = s0 + k;
;       int j = dirsel == 0 ? step : (step < 8 ? 7 - step : 79 - step);
;       er[k] = E[(size_t)j * 256]; ei[k] = E[(size_t)j * 256 + 64];
;     }
; #pragma unroll
;     for (int k = 0; k < 8; k++) {
;       int step = s0 + k;
;       int j = dirsel == 0 ? step : (step < 8 ? 7 - step : 79 - step);
;       S[(size_t)j * 768] = f2bf(sr); S[(size_t)j * 768 + 64] = f2bf(si);
;       float nr = are * sr - aim * si + er[k], ni = are * si + aim * sr + ei[k];
;       sr = nr; si = ni;
;     }
;   }
	v_pk_add_f32 v[4:5], v[60:61], v[20:21]
	v_mul_lo_u32 v12, v46, s9
	v_cvt_pk_bf16_f32 v14, v4, v4
	v_lshl_add_u64 v[16:17], v[12:13], 1, v[8:9]
	global_store_short v[16:17], v14, off
	v_cvt_pk_bf16_f32 v14, v5, v5
	global_store_short v[16:17], v14, off offset:128
	v_pk_mul_f32 v[18:19], v[2:3], v[4:5]
	s_nop 0
	v_pk_fma_f32 v[20:21], v[0:1], v[4:5], v[18:19] op_sel:[0,0,1] op_sel_hi:[1,1,0] neg_lo:[0,0,1] neg_hi:[0,0,1]
	v_pk_fma_f32 v[4:5], v[0:1], v[4:5], v[18:19] op_sel:[0,0,1] op_sel_hi:[1,1,0]
	s_nop 0
	v_mov_b32_e32 v21, v5
	s_waitcnt vmcnt(48)
	v_pk_add_f32 v[4:5], v[62:63], v[20:21]
	v_mul_lo_u32 v12, v48, s9
	v_cvt_pk_bf16_f32 v14, v4, v4
	v_lshl_add_u64 v[16:17], v[12:13], 1, v[8:9]
	global_store_short v[16:17], v14, off
	v_cvt_pk_bf16_f32 v14, v5, v5
	global_store_short v[16:17], v14, off offset:128
	v_pk_mul_f32 v[18:19], v[2:3], v[4:5]
	s_nop 0
	v_pk_fma_f32 v[20:21], v[0:1], v[4:5], v[18:19] op_sel:[0,0,1] op_sel_hi:[1,1,0] neg_lo:[0,0,1] neg_hi:[0,0,1]
	v_pk_fma_f32 v[4:5], v[0:1], v[4:5], v[18:19] op_sel:[0,0,1] op_sel_hi:[1,1,0]
	s_nop 0
	v_mov_b32_e32 v21, v5
	s_waitcnt vmcnt(48)
	v_pk_add_f32 v[4:5], v[64:65], v[20:21]
	v_mul_lo_u32 v12, v50, s9
	v_cvt_pk_bf16_f32 v14, v4, v4
	v_lshl_add_u64 v[16:17], v[12:13], 1, v[8:9]
	global_store_short v[16:17], v14, off
	v_cvt_pk_bf16_f32 v14, v5, v5
	global_store_short v[16:17], v14, off offset:128
	v_pk_mul_f32 v[18:19], v[2:3], v[4:5]
	s_nop 0
	v_pk_fma_f32 v[20:21], v[0:1], v[4:5], v[18:19] op_sel:[0,0,1] op_sel_hi:[1,1,0] neg_lo:[0,0,1] neg_hi:[0,0,1]
	v_pk_fma_f32 v[4:5], v[0:1], v[4:5], v[18:19] op_sel:[0,0,1] op_sel_hi:[1,1,0]
	s_nop 0
	v_mov_b32_e32 v21, v5
	s_waitcnt vmcnt(48)
	v_pk_add_f32 v[4:5], v[66:67], v[20:21]
	v_mul_lo_u32 v12, v52, s9
	v_cvt_pk_bf16_f32 v14, v4, v4
	v_lshl_add_u64 v[16:17], v[12:13], 1, v[8:9]
	global_store_short v[16:17], v14, off
	v_cvt_pk_bf16_f32 v14, v5, v5
	global_store_short v[16:17], v14, off offset:128
	v_pk_mul_f32 v[18:19], v[2:3], v[4:5]
	s_nop 0
	v_pk_fma_f32 v[20:21], v[0:1], v[4:5], v[18:19] op_sel:[0,0,1] op_sel_hi:[1,1,0] neg_lo:[0,0,1] neg_hi:[0,0,1]
	v_pk_fma_f32 v[4:5], v[0:1], v[4:5], v[18:19] op_sel:[0,0,1] op_sel_hi:[1,1,0]
	s_nop 0
	v_mov_b32_e32 v21, v5
	s_waitcnt vmcnt(48)
	v_pk_add_f32 v[4:5], v[68:69], v[20:21]
	v_mul_lo_u32 v12, v54, s9
	v_cvt_pk_bf16_f32 v14, v4, v4
	v_lshl_add_u64 v[16:17], v[12:13], 1, v[8:9]
	global_store_short v[16:17], v14, off
	v_cvt_pk_bf16_f32 v14, v5, v5
	global_store_short v[16:17], v14, off offset:128
	v_pk_mul_f32 v[18:19], v[2:3], v[4:5]
	s_nop 0
	v_pk_fma_f32 v[20:21], v[0:1], v[4:5], v[18:19] op_sel:[0,0,1] op_sel_hi:[1,1,0] neg_lo:[0,0,1] neg_hi:[0,0,1]
	v_pk_fma_f32 v[4:5], v[0:1], v[4:5], v[18:19] op_sel:[0,0,1] op_sel_hi:[1,1,0]
	s_nop 0
	v_mov_b32_e32 v21, v5
	s_waitcnt vmcnt(48)
	v_pk_add_f32 v[4:5], v[70:71], v[20:21]
	v_mul_lo_u32 v12, v56, s9
	v_cvt_pk_bf16_f32 v14, v4, v4
	v_lshl_add_u64 v[16:17], v[12:13], 1, v[8:9]
	global_store_short v[16:17], v14, off
	v_cvt_pk_bf16_f32 v14, v5, v5
	global_store_short v[16:17], v14, off offset:128
	v_pk_mul_f32 v[18:19], v[2:3], v[4:5]
	s_nop 0
	v_pk_fma_f32 v[20:21], v[0:1], v[4:5], v[18:19] op_sel:[0,0,1] op_sel_hi:[1,1,0] neg_lo:[0,0,1] neg_hi:[0,0,1]
	v_pk_fma_f32 v[4:5], v[0:1], v[4:5], v[18:19] op_sel:[0,0,1] op_sel_hi:[1,1,0]
	s_nop 0
	v_mov_b32_e32 v21, v5
	s_waitcnt vmcnt(48)
	v_pk_add_f32 v[4:5], v[72:73], v[20:21]
	v_mul_lo_u32 v12, v58, s9
	v_cvt_pk_bf16_f32 v14, v4, v4
	v_lshl_add_u64 v[16:17], v[12:13], 1, v[8:9]
	global_store_short v[16:17], v14, off
	v_cvt_pk_bf16_f32 v14, v5, v5
	global_store_short v[16:17], v14, off offset:128
	v_pk_mul_f32 v[18:19], v[2:3], v[4:5]
	s_nop 0
	v_pk_fma_f32 v[20:21], v[0:1], v[4:5], v[18:19] op_sel:[0,0,1] op_sel_hi:[1,1,0] neg_lo:[0,0,1] neg_hi:[0,0,1]
	v_pk_fma_f32 v[4:5], v[0:1], v[4:5], v[18:19] op_sel:[0,0,1] op_sel_hi:[1,1,0]
	s_nop 0
	v_mov_b32_e32 v21, v5
	s_waitcnt vmcnt(48)
	v_pk_add_f32 v[4:5], v[74:75], v[20:21]
	s_waitcnt vmcnt(32)
	v_mov_b32_e32 v44, 64
	v_cndmask_b32_e32 v44, 15, v44, vcc
	v_lshlrev_b32_e32 v10, 10, v44
	v_mov_b32_e32 v11, 0
	v_lshl_add_u64 v[10:11], v[6:7], 0, v[10:11]
	global_load_dword v60, v[10:11], off
	global_load_dword v61, v[10:11], off offset:256
	v_mov_b32_e32 v46, 0x41
	v_cndmask_b32_e32 v46, 14, v46, vcc
	v_lshlrev_b32_e32 v10, 10, v46
	v_mov_b32_e32 v11, 0
	v_lshl_add_u64 v[10:11], v[6:7], 0, v[10:11]
	global_load_dword v62, v[10:11], off
	global_load_dword v63, v[10:11], off offset:256
	v_mov_b32_e32 v48, 0x42
	v_cndmask_b32_e32 v48, 13, v48, vcc
	v_lshlrev_b32_e32 v10, 10, v48
	v_mov_b32_e32 v11, 0
	v_lshl_add_u64 v[10:11], v[6:7], 0, v[10:11]
	global_load_dword v64, v[10:11], off
	global_load_dword v65, v[10:11], off offset:256
	v_mov_b32_e32 v50, 0x43
	v_cndmask_b32_e32 v50, 12, v50, vcc
	v_lshlrev_b32_e32 v10, 10, v50
	v_mov_b32_e32 v11, 0
	v_lshl_add_u64 v[10:11], v[6:7], 0, v[10:11]
	global_load_dword v66, v[10:11], off
	global_load_dword v67, v[10:11], off offset:256
	v_mov_b32_e32 v52, 0x44
	v_cndmask_b32_e32 v52, 11, v52, vcc
	v_lshlrev_b32_e32 v10, 10, v52
	v_mov_b32_e32 v11, 0
	v_lshl_add_u64 v[10:11], v[6:7], 0, v[10:11]
	global_load_dword v68, v[10:11], off
	global_load_dword v69, v[10:11], off offset:256
	v_mov_b32_e32 v54, 0x45
	v_cndmask_b32_e32 v54, 10, v54, vcc
	v_lshlrev_b32_e32 v10, 10, v54
	v_mov_b32_e32 v11, 0
	v_lshl_add_u64 v[10:11], v[6:7], 0, v[10:11]
	global_load_dword v70, v[10:11], off
	global_load_dword v71, v[10:11], off offset:256
	v_mov_b32_e32 v56, 0x46
	v_cndmask_b32_e32 v56, 9, v56, vcc
	v_lshlrev_b32_e32 v10, 10, v56
	v_mov_b32_e32 v11, 0
	v_lshl_add_u64 v[10:11], v[6:7], 0, v[10:11]
	global_load_dword v72, v[10:11], off
	global_load_dword v73, v[10:11], off offset:256
	v_mov_b32_e32 v58, 0x47
	v_cndmask_b32_e32 v58, 8, v58, vcc
	v_lshlrev_b32_e32 v10, 10, v58
	v_mov_b32_e32 v11, 0
	v_lshl_add_u64 v[10:11], v[6:7], 0, v[10:11]
	global_load_dword v74, v[10:11], off
	global_load_dword v75, v[10:11], off offset:256
	v_mul_lo_u32 v12, v76, s9
	v_cvt_pk_bf16_f32 v14, v4, v4
	v_lshl_add_u64 v[16:17], v[12:13], 1, v[8:9]
	global_store_short v[16:17], v14, off
	v_cvt_pk_bf16_f32 v14, v5, v5
	global_store_short v[16:17], v14, off offset:128
	v_pk_mul_f32 v[18:19], v[2:3], v[4:5]
	s_nop 0
	v_pk_fma_f32 v[20:21], v[0:1], v[4:5], v[18:19] op_sel:[0,0,1] op_sel_hi:[1,1,0] neg_lo:[0,0,1] neg_hi:[0,0,1]
	v_pk_fma_f32 v[4:5], v[0:1], v[4:5], v[18:19] op_sel:[0,0,1] op_sel_hi:[1,1,0]
	s_nop 0
	v_mov_b32_e32 v21, v5
	s_waitcnt vmcnt(48)
; __device__ __forceinline__ u16 f2bf(float f) { unsigned r; asm("v_cvt_pk_bf16_f32 %0, %1, %1" : "=v"(r) : "v"(f)); return (u16)r; }
; __device__ __forceinline__ void s5scan_item(const Params& p, int layer, int item) {
;     ...
;   for (int s0 = 0; s0 < 72; s0 += 8) {
;     float er[8], ei[8];
; #pragma unroll
;     for (int k = 0; k < 8; k++) {
;       int step = s0 + k;
;       int j = dirsel == 0 ? step : (step < 8 ? 7 - step : 79 - step);
;       er[k] = E[(size_t)j * 256]; ei[k] = E[(size_t)j * 256 + 64];
;     }
; #pragma unroll
;     for (int k = 0; k < 8; k++) {
;       int step = s0 + k;
;       int j = dirsel == 0 ? step : (step < 8 ? 7 - step : 79 - step);
;       S[(size_t)j * 768] = f2bf(sr); S[(size_t)j * 768 + 64] = f2bf(si);
;       float nr = are * sr - aim * si + er[k], ni = are * si + aim * sr + ei[k];
;       sr = nr; si = ni;
;     }
;   }
	v_pk_add_f32 v[4:5], v[92:93], v[20:21]
	v_mul_lo_u32 v12, v78, s9
	v_cvt_pk_bf16_f32 v14, v4, v4
	v_lshl_add_u64 v[16:17], v[12:13], 1, v[8:9]
	global_store_short v[16:17], v14, off
	v_cvt_pk_bf16_f32 v14, v5, v5
	global_store_short v[16:17], v14, off offset:128
	v_pk_mul_f32 v[18:19], v[2:3], v[4:5]
	s_nop 0
	v_pk_fma_f32 v[20:21], v[0:1], v[4:5], v[18:19] op_sel:[0,0,1] op_sel_hi:[1,1,0] neg_lo:[0,0,1] neg_hi:[0,0,1]
	v_pk_fma_f32 v[4:5], v[0:1], v[4:5], v[18:19] op_sel:[0,0,1] op_sel_hi:[1,1,0]
	s_nop 0
	v_mov_b32_e32 v21, v5
	s_waitcnt vmcnt(48)
	v_pk_add_f32 v[4:5], v[94:95], v[20:21]
	v_mul_lo_u32 v12, v80, s9
	v_cvt_pk_bf16_f32 v14, v4, v4
	v_lshl_add_u64 v[16:17], v[12:13], 1, v[8:9]
	global_store_short v[16:17], v14, off
	v_cvt_pk_bf16_f32 v14, v5, v5
	global_store_short v[16:17], v14, off offset:128
	v_pk_mul_f32 v[18:19], v[2:3], v[4:5]
	s_nop 0
	v_pk_fma_f32 v[20:21], v[0:1], v[4:5], v[18:19] op_sel:[0,0,1] op_sel_hi:[1,1,0] neg_lo:[0,0,1] neg_hi:[0,0,1]
	v_pk_fma_f32 v[4:5], v[0:1], v[4:5], v[18:19] op_sel:[0,0,1] op_sel_hi:[1,1,0]
	s_nop 0
	v_mov_b32_e32 v21, v5
	s_waitcnt vmcnt(48)
	v_pk_add_f32 v[4:5], v[96:97], v[20:21]
	v_mul_lo_u32 v12, v82, s9
	v_cvt_pk_bf16_f32 v14, v4, v4
	v_lshl_add_u64 v[16:17], v[12:13], 1, v[8:9]
	global_store_short v[16:17], v14, off
	v_cvt_pk_bf16_f32 v14, v5, v5
	global_store_short v[16:17], v14, off offset:128
	v_pk_mul_f32 v[18:19], v[2:3], v[4:5]
	s_nop 0
	v_pk_fma_f32 v[20:21], v[0:1], v[4:5], v[18:19] op_sel:[0,0,1] op_sel_hi:[1,1,0] neg_lo:[0,0,1] neg_hi:[0,0,1]
	v_pk_fma_f32 v[4:5], v[0:1], v[4:5], v[18:19] op_sel:[0,0,1] op_sel_hi:[1,1,0]
	s_nop 0
	v_mov_b32_e32 v21, v5
	s_waitcnt vmcnt(48)
	v_pk_add_f32 v[4:5], v[98:99], v[20:21]
	v_mul_lo_u32 v12, v84, s9
	v_cvt_pk_bf16_f32 v14, v4, v4
	v_lshl_add_u64 v[16:17], v[12:13], 1, v[8:9]
	global_store_short v[16:17], v14, off
	v_cvt_pk_bf16_f32 v14, v5, v5
	global_store_short v[16:17], v14, off offset:128
	v_pk_mul_f32 v[18:19], v[2:3], v[4:5]
	s_nop 0
	v_pk_fma_f32 v[20:21], v[0:1], v[4:5], v[18:19] op_sel:[0,0,1] op_sel_hi:[1,1,0] neg_lo:[0,0,1] neg_hi:[0,0,1]
	v_pk_fma_f32 v[4:5], v[0:1], v[4:5], v[18:19] op_sel:[0,0,1] op_sel_hi:[1,1,0]
	s_nop 0
	v_mov_b32_e32 v21, v5
	s_waitcnt vmcnt(48)
	v_pk_add_f32 v[4:5], v[100:101], v[20:21]
	v_mul_lo_u32 v12, v86, s9
	v_cvt_pk_bf16_f32 v14, v4, v4
	v_lshl_add_u64 v[16:17], v[12:13], 1, v[8:9]
	global_store_short v[16:17], v14, off
	v_cvt_pk_bf16_f32 v14, v5, v5
	global_store_short v[16:17], v14, off offset:128
	v_pk_mul_f32 v[18:19], v[2:3], v[4:5]
	s_nop 0
	v_pk_fma_f32 v[20:21], v[0:1], v[4:5], v[18:19] op_sel:[0,0,1] op_sel_hi:[1,1,0] neg_lo:[0,0,1] neg_hi:[0,0,1]
	v_pk_fma_f32 v[4:5], v[0:1], v[4:5], v[18:19] op_sel:[0,0,1] op_sel_hi:[1,1,0]
	s_nop 0
	v_mov_b32_e32 v21, v5
	s_waitcnt vmcnt(48)
	v_pk_add_f32 v[4:5], v[102:103], v[20:21]
	v_mul_lo_u32 v12, v88, s9
	v_cvt_pk_bf16_f32 v14, v4, v4
	v_lshl_add_u64 v[16:17], v[12:13], 1, v[8:9]
	global_store_short v[16:17], v14, off
	v_cvt_pk_bf16_f32 v14, v5, v5
	global_store_short v[16:17], v14, off offset:128
	v_pk_mul_f32 v[18:19], v[2:3], v[4:5]
	s_nop 0
	v_pk_fma_f32 v[20:21], v[0:1], v[4:5], v[18:19] op_sel:[0,0,1] op_sel_hi:[1,1,0] neg_lo:[0,0,1] neg_hi:[0,0,1]
	v_pk_fma_f32 v[4:5], v[0:1], v[4:5], v[18:19] op_sel:[0,0,1] op_sel_hi:[1,1,0]
	s_nop 0
	v_mov_b32_e32 v21, v5
	s_waitcnt vmcnt(48)
	v_pk_add_f32 v[4:5], v[104:105], v[20:21]
	v_mul_lo_u32 v12, v90, s9
	v_cvt_pk_bf16_f32 v14, v4, v4
	v_lshl_add_u64 v[16:17], v[12:13], 1, v[8:9]
	global_store_short v[16:17], v14, off
	v_cvt_pk_bf16_f32 v14, v5, v5
	global_store_short v[16:17], v14, off offset:128
	v_pk_mul_f32 v[18:19], v[2:3], v[4:5]
	s_nop 0
	v_pk_fma_f32 v[20:21], v[0:1], v[4:5], v[18:19] op_sel:[0,0,1] op_sel_hi:[1,1,0] neg_lo:[0,0,1] neg_hi:[0,0,1]
	v_pk_fma_f32 v[4:5], v[0:1], v[4:5], v[18:19] op_sel:[0,0,1] op_sel_hi:[1,1,0]
	s_nop 0
	v_mov_b32_e32 v21, v5
	s_waitcnt vmcnt(48)
	v_pk_add_f32 v[4:5], v[106:107], v[20:21]
	s_waitcnt vmcnt(32)
	v_mul_lo_u32 v12, v44, s9
	v_cvt_pk_bf16_f32 v14, v4, v4
	v_lshl_add_u64 v[16:17], v[12:13], 1, v[8:9]
	global_store_short v[16:17], v14, off
	v_cvt_pk_bf16_f32 v14, v5, v5
	global_store_short v[16:17], v14, off offset:128
	v_pk_mul_f32 v[18:19], v[2:3], v[4:5]
	s_nop 0
	v_pk_fma_f32 v[20:21], v[0:1], v[4:5], v[18:19] op_sel:[0,0,1] op_sel_hi:[1,1,0] neg_lo:[0,0,1] neg_hi:[0,0,1]
	v_pk_fma_f32 v[4:5], v[0:1], v[4:5], v[18:19] op_sel:[0,0,1] op_sel_hi:[1,1,0]
	s_nop 0
	v_mov_b32_e32 v21, v5
	s_waitcnt vmcnt(32)
; __device__ __forceinline__ u16 f2bf(float f) { unsigned r; asm("v_cvt_pk_bf16_f32 %0, %1, %1" : "=v"(r) : "v"(f)); return (u16)r; }
; __device__ __forceinline__ unsigned xb_add(unsigned* p, unsigned v) { return __hip_atomic_fetch_add(p, v, __ATOMIC_RELAXED, __HIP_MEMORY_SCOPE_AGENT); }
; __device__ __forceinline__ void s5scan_item(const Params& p, int layer, int item) {
;     ...
;   for (int s0 = 0; s0 < 72; s0 += 8) {
;     float er[8], ei[8];
; #pragma unroll
;     for (int k = 0; k < 8; k++) {
;       int step = s0 + k;
;       int j = dirsel == 0 ? step : (step < 8 ? 7 - step : 79 - step);
;       er[k] = E[(size_t)j * 256]; ei[k] = E[(size_t)j * 256 + 64];
;     }
; #pragma unroll
;     for (int k = 0; k < 8; k++) {
;       int step = s0 + k;
;       int j = dirsel == 0 ? step : (step < 8 ? 7 - step : 79 - step);
;       S[(size_t)j * 768] = f2bf(sr); S[(size_t)j * 768 + 64] = f2bf(si);
;       float nr = are * sr - aim * si + er[k], ni = are * si + aim * sr + ei[k];
;       sr = nr; si = ni;
;     }
;   }
; __global__ void __launch_bounds__(512, 2) fwd_megakernel(Params p) {
;     ...
;         asm volatile("s_waitcnt vmcnt(0)" ::: "memory");
;         __syncthreads();
;         if (threadIdx.x == 0) {
;           __builtin_amdgcn_fence(__ATOMIC_RELEASE, "agent");
;           asm volatile("s_waitcnt vmcnt(0)" ::: "memory");
;           (void)xb_add(s5flag + 32, 1u);
	v_pk_add_f32 v[4:5], v[60:61], v[20:21]
	v_mul_lo_u32 v12, v46, s9
	v_cvt_pk_bf16_f32 v14, v4, v4
	v_lshl_add_u64 v[16:17], v[12:13], 1, v[8:9]
	global_store_short v[16:17], v14, off
	v_cvt_pk_bf16_f32 v14, v5, v5
	global_store_short v[16:17], v14, off offset:128
	v_pk_mul_f32 v[18:19], v[2:3], v[4:5]
	s_nop 0
	v_pk_fma_f32 v[20:21], v[0:1], v[4:5], v[18:19] op_sel:[0,0,1] op_sel_hi:[1,1,0] neg_lo:[0,0,1] neg_hi:[0,0,1]
	v_pk_fma_f32 v[4:5], v[0:1], v[4:5], v[18:19] op_sel:[0,0,1] op_sel_hi:[1,1,0]
	s_nop 0
	v_mov_b32_e32 v21, v5
	s_waitcnt vmcnt(32)
	v_pk_add_f32 v[4:5], v[62:63], v[20:21]
	v_mul_lo_u32 v12, v48, s9
	v_cvt_pk_bf16_f32 v14, v4, v4
	v_lshl_add_u64 v[16:17], v[12:13], 1, v[8:9]
	global_store_short v[16:17], v14, off
	v_cvt_pk_bf16_f32 v14, v5, v5
	global_store_short v[16:17], v14, off offset:128
	v_pk_mul_f32 v[18:19], v[2:3], v[4:5]
	s_nop 0
	v_pk_fma_f32 v[20:21], v[0:1], v[4:5], v[18:19] op_sel:[0,0,1] op_sel_hi:[1,1,0] neg_lo:[0,0,1] neg_hi:[0,0,1]
	v_pk_fma_f32 v[4:5], v[0:1], v[4:5], v[18:19] op_sel:[0,0,1] op_sel_hi:[1,1,0]
	s_nop 0
	v_mov_b32_e32 v21, v5
	s_waitcnt vmcnt(32)
	v_pk_add_f32 v[4:5], v[64:65], v[20:21]
	v_mul_lo_u32 v12, v50, s9
	v_cvt_pk_bf16_f32 v14, v4, v4
	v_lshl_add_u64 v[16:17], v[12:13], 1, v[8:9]
	global_store_short v[16:17], v14, off
	v_cvt_pk_bf16_f32 v14, v5, v5
	global_store_short v[16:17], v14, off offset:128
	v_pk_mul_f32 v[18:19], v[2:3], v[4:5]
	s_nop 0
	v_pk_fma_f32 v[20:21], v[0:1], v[4:5], v[18:19] op_sel:[0,0,1] op_sel_hi:[1,1,0] neg_lo:[0,0,1] neg_hi:[0,0,1]
	v_pk_fma_f32 v[4:5], v[0:1], v[4:5], v[18:19] op_sel:[0,0,1] op_sel_hi:[1,1,0]
	s_nop 0
	v_mov_b32_e32 v21, v5
	s_waitcnt vmcnt(32)
	v_pk_add_f32 v[4:5], v[66:67], v[20:21]
	v_mul_lo_u32 v12, v52, s9
	v_cvt_pk_bf16_f32 v14, v4, v4
	v_lshl_add_u64 v[16:17], v[12:13], 1, v[8:9]
	global_store_short v[16:17], v14, off
	v_cvt_pk_bf16_f32 v14, v5, v5
	global_store_short v[16:17], v14, off offset:128
	v_pk_mul_f32 v[18:19], v[2:3], v[4:5]
	s_nop 0
	v_pk_fma_f32 v[20:21], v[0:1], v[4:5], v[18:19] op_sel:[0,0,1] op_sel_hi:[1,1,0] neg_lo:[0,0,1] neg_hi:[0,0,1]
	v_pk_fma_f32 v[4:5], v[0:1], v[4:5], v[18:19] op_sel:[0,0,1] op_sel_hi:[1,1,0]
	s_nop 0
	v_mov_b32_e32 v21, v5
	s_waitcnt vmcnt(32)
	v_pk_add_f32 v[4:5], v[68:69], v[20:21]
	v_mul_lo_u32 v12, v54, s9
	v_cvt_pk_bf16_f32 v14, v4, v4
	v_lshl_add_u64 v[16:17], v[12:13], 1, v[8:9]
	global_store_short v[16:17], v14, off
	v_cvt_pk_bf16_f32 v14, v5, v5
	global_store_short v[16:17], v14, off offset:128
	v_pk_mul_f32 v[18:19], v[2:3], v[4:5]
	s_nop 0
	v_pk_fma_f32 v[20:21], v[0:1], v[4:5], v[18:19] op_sel:[0,0,1] op_sel_hi:[1,1,0] neg_lo:[0,0,1] neg_hi:[0,0,1]
	v_pk_fma_f32 v[4:5], v[0:1], v[4:5], v[18:19] op_sel:[0,0,1] op_sel_hi:[1,1,0]
	s_nop 0
	v_mov_b32_e32 v21, v5
	s_waitcnt vmcnt(32)
	v_pk_add_f32 v[4:5], v[70:71], v[20:21]
	v_mul_lo_u32 v12, v56, s9
	v_cvt_pk_bf16_f32 v14, v4, v4
	v_lshl_add_u64 v[16:17], v[12:13], 1, v[8:9]
	global_store_short v[16:17], v14, off
	v_cvt_pk_bf16_f32 v14, v5, v5
	global_store_short v[16:17], v14, off offset:128
	v_pk_mul_f32 v[18:19], v[2:3], v[4:5]
	s_nop 0
	v_pk_fma_f32 v[20:21], v[0:1], v[4:5], v[18:19] op_sel:[0,0,1] op_sel_hi:[1,1,0] neg_lo:[0,0,1] neg_hi:[0,0,1]
	v_pk_fma_f32 v[4:5], v[0:1], v[4:5], v[18:19] op_sel:[0,0,1] op_sel_hi:[1,1,0]
	s_nop 0
	v_mov_b32_e32 v21, v5
	s_waitcnt vmcnt(32)
	v_pk_add_f32 v[4:5], v[72:73], v[20:21]
	v_mul_lo_u32 v12, v58, s9
	v_cvt_pk_bf16_f32 v14, v4, v4
	v_lshl_add_u64 v[16:17], v[12:13], 1, v[8:9]
	global_store_short v[16:17], v14, off
	v_cvt_pk_bf16_f32 v14, v5, v5
	global_store_short v[16:17], v14, off offset:128
	v_pk_mul_f32 v[18:19], v[2:3], v[4:5]
	s_nop 0
	v_pk_fma_f32 v[20:21], v[0:1], v[4:5], v[18:19] op_sel:[0,0,1] op_sel_hi:[1,1,0] neg_lo:[0,0,1] neg_hi:[0,0,1]
	v_pk_fma_f32 v[4:5], v[0:1], v[4:5], v[18:19] op_sel:[0,0,1] op_sel_hi:[1,1,0]
	s_nop 0
	v_mov_b32_e32 v21, v5
	s_waitcnt vmcnt(32)
	v_pk_add_f32 v[4:5], v[74:75], v[20:21]
	s_waitcnt vmcnt(0)
	s_waitcnt lgkmcnt(0)
	s_barrier
	s_mov_b64 s[4:5], exec
	v_readlane_b32 s6, v254, 1
	v_readlane_b32 s7, v254, 2
	s_and_b64 s[6:7], s[4:5], s[6:7]
	s_mov_b64 exec, s[6:7]
	s_cbranch_execz .LBB0_587
	buffer_wbl2 sc1
	s_waitcnt vmcnt(0)
	s_waitcnt vmcnt(0)
	flat_atomic_add v[128:129], v230 offset:128

; __device__ __forceinline__ unsigned pack2(float a, float b) { unsigned r; asm("v_cvt_pk_bf16_f32 %0, %1, %2" : "=v"(r) : "v"(a), "v"(b)); return r; }
; #define layer launder_s(layer_)
; __device__ __forceinline__ void route_item(const Params& p, int tile, unsigned char* smem) {
;     ...
;     int row = tile * 64 + rl;
;     const float* src = (const float*)(p.ws + O_XRES) + (size_t)row * D;
;     int m = row >> 11;
;     const float* md = MOD + (size_t)(layer * 9 + m) * 6144 + 3072;
;     float4 v[4];
;     float ss = 0.f;
; #pragma unroll
;     for (int q = 0; q < 4; q++) {
;       v[q] = *(const float4*)(src + q * 256 + lane * 4);
;       ss += v[q].x * v[q].x + v[q].y * v[q].y + v[q].z * v[q].z + v[q].w * v[q].w;
;       *(float4*)(p.out + (size_t)row * D + q * 256 + lane * 4) = v[q];
;     }
;     ss = wave_sum(ss);
;     float rstd = rsqrtf(ss * (1.0f / 1024.0f) + EPS);
;     float lg[8];
; #pragma unroll
;     for (int e = 0; e < 8; e++) lg[e] = 0.f;
; #pragma unroll
;     for (int q = 0; q < 4; q++) {
;       int cidx = q * 256 + lane * 4;
;       float4 gg = *(const float4*)(g + cidx);
;       float4 sh = *(const float4*)(md + cidx);
;       float4 sc = *(const float4*)(md + 1024 + cidx);
;       float o[4];
;       o[0] = v[q].x * rstd * gg.x * (1.f + sc.x) + sh.x;
;       o[1] = v[q].y * rstd * gg.y * (1.f + sc.y) + sh.y;
;       o[2] = v[q].z * rstd * gg.z * (1.f + sc.z) + sh.z;
;       o[3] = v[q].w * rstd * gg.w * (1.f + sc.w) + sh.w;
;       uint2 ob; ob.x = pack2(o[0], o[1]); ob.y = pack2(o[2], o[3]);
;       *(uint2*)(XN + (size_t)row * D + cidx) = ob;
; #pragma unroll
;       for (int u = 0; u < 4; u++) {
;         float4 r0 = *(const float4*)(rw + (cidx + u) * 8);
;         float4 r1 = *(const float4*)(rw + (cidx + u) * 8 + 4);
;         lg[0] += o[u] * r0.x; lg[1] += o[u] * r0.y; lg[2] += o[u] * r0.z; lg[3] += o[u] * r0.w;
.LBB0_1006:
	v_mov_b64_e32 v[44:45], s[6:7]
	s_waitcnt lgkmcnt(0)
	global_load_dwordx4 v[0:3], v[44:45], off offset:336
	v_ashrrev_i32_e32 v35, 31, v34
	v_lshlrev_b64 v[46:47], 12, v[34:35]
	v_ashrrev_i32_e32 v4, 11, v34
	v_add_u32_e32 v4, 9, v4
	v_mul_hi_i32_i24_e32 v5, 0x6000, v4
	v_mul_i32_i24_e32 v4, 0x6000, v4
	v_lshl_add_u64 v[42:43], v[18:19], 0, v[4:5]
	s_mov_b64 s[10:11], 0x6c03000
	s_waitcnt vmcnt(0) lgkmcnt(0)
	v_lshl_add_u64 v[0:1], v[0:1], 0, v[46:47]
	v_lshl_add_u64 v[0:1], v[0:1], 0, v[160:161]
	global_load_dwordx4 v[12:15], v[0:1], off
	global_load_dwordx4 v[8:11], v[0:1], off offset:1024
	global_load_dwordx4 v[68:71], v[0:1], off offset:2048
	global_load_dwordx4 v[72:75], v[0:1], off offset:3072
	v_lshl_add_u64 v[2:3], v[2:3], 0, v[46:47]
	v_lshl_add_u64 v[44:45], v[2:3], 0, v[160:161]
	s_waitcnt vmcnt(3)
	global_store_dwordx4 v[44:45], v[12:15], off
	s_waitcnt vmcnt(3)
	global_store_dwordx4 v[44:45], v[8:11], off offset:1024
	s_waitcnt vmcnt(3)
	global_store_dwordx4 v[44:45], v[68:71], off offset:2048
	s_waitcnt vmcnt(3)
	global_store_dwordx4 v[44:45], v[72:75], off offset:3072
	v_mov_b32_e32 v6, v13
	v_mov_b32_e32 v4, v12
	v_mov_b32_e32 v58, v15
	v_mov_b32_e32 v7, v9
	v_mov_b32_e32 v5, v8
	v_pk_mul_f32 v[6:7], v[6:7], v[6:7]
	v_pk_fma_f32 v[4:5], v[4:5], v[4:5], v[6:7]
	v_mov_b32_e32 v6, v14
	v_mov_b32_e32 v7, v10
	v_mov_b32_e32 v59, v11
	v_pk_fma_f32 v[4:5], v[6:7], v[6:7], v[4:5]
	v_pk_fma_f32 v[58:59], v[58:59], v[58:59], v[4:5]
	v_add_f32_e32 v37, v58, v59
	v_mov_b32_e32 v4, v68
	v_mov_b32_e32 v5, v69
	v_mov_b32_e32 v6, v70
	v_mov_b32_e32 v7, v71
	v_mov_b32_e32 v0, v72
	v_mov_b32_e32 v1, v73
	v_mov_b32_e32 v2, v74
	v_mov_b32_e32 v3, v75
	v_mov_b32_e32 v60, v5
	v_mov_b32_e32 v62, v7
	v_mov_b32_e32 v46, v4
	v_mov_b32_e32 v61, v1
	v_mov_b32_e32 v47, v0
	v_pk_mul_f32 v[60:61], v[60:61], v[60:61]
	v_mov_b32_e32 v63, v3
	v_pk_fma_f32 v[46:47], v[46:47], v[46:47], v[60:61]
	v_mov_b32_e32 v60, v6
	v_mov_b32_e32 v61, v2
	v_pk_fma_f32 v[46:47], v[60:61], v[60:61], v[46:47]
	v_pk_fma_f32 v[46:47], v[62:63], v[62:63], v[46:47]
	v_lshl_add_u64 v[44:45], v[42:43], 0, s[10:11]
	v_add_f32_e32 v37, v37, v46
	s_mov_b64 s[10:11], 0x6c04000
	v_add_f32_e32 v37, v37, v47
	v_lshl_add_u64 v[46:47], v[42:43], 0, s[10:11]
	v_lshl_add_u64 v[42:43], v[44:45], 0, v[160:161]
	global_load_dwordx4 v[68:71], v[42:43], off
	v_lshl_add_u64 v[42:43], v[46:47], 0, v[160:161]
	global_load_dwordx4 v[58:61], v[24:25], off
	global_load_dwordx4 v[62:65], v[42:43], off
	v_mov_b32_e32 v121, 0
	global_load_dwordx4 v[84:87], v[26:27], off
	v_mov_b32_e32 v120, v36
	v_lshl_add_u64 v[122:123], v[44:45], 0, v[120:121]
	global_load_dwordx4 v[88:91], v[122:123], off
	v_mov_b32_e32 v120, v36
	v_lshl_add_u64 v[122:123], v[46:47], 0, v[120:121]
	global_load_dwordx4 v[92:95], v[122:123], off
	global_load_dwordx4 v[96:99], v[28:29], off
	v_mov_b32_e32 v120, v38
	v_lshl_add_u64 v[122:123], v[46:47], 0, v[120:121]
	global_load_dwordx4 v[100:103], v[122:123], off
	v_mov_b32_e32 v120, v38
	v_lshl_add_u64 v[122:123], v[44:45], 0, v[120:121]
	global_load_dwordx4 v[104:107], v[122:123], off
	global_load_dwordx4 v[108:111], v[30:31], off
	v_mov_b32_e32 v120, v40
	v_lshl_add_u64 v[122:123], v[44:45], 0, v[120:121]
	global_load_dwordx4 v[112:115], v[122:123], off
	v_mov_b32_e32 v120, v40
	v_lshl_add_u64 v[122:123], v[46:47], 0, v[120:121]
	global_load_dwordx4 v[116:119], v[122:123], off
	ds_bpermute_b32 v39, v17, v37
	s_waitcnt lgkmcnt(0)
	v_add_f32_e32 v37, v37, v39
	ds_bpermute_b32 v39, v48, v37
	s_waitcnt lgkmcnt(0)
	v_add_f32_e32 v37, v37, v39
	ds_bpermute_b32 v39, v49, v37
	s_waitcnt lgkmcnt(0)
	v_add_f32_e32 v37, v37, v39
	ds_bpermute_b32 v39, v50, v37
	s_waitcnt lgkmcnt(0)
	v_add_f32_e32 v37, v37, v39
	ds_bpermute_b32 v39, v51, v37
	s_waitcnt lgkmcnt(0)
	v_add_f32_e32 v37, v37, v39
	ds_bpermute_b32 v39, v52, v37
	s_waitcnt lgkmcnt(0)
	v_add_f32_e32 v37, v37, v39
	v_fmamk_f32 v37, v37, 0x3a800000, v229
	v_cmp_gt_f32_e32 vcc, s89, v37
	v_mul_f32_e32 v39, 0x4b800000, v37
	s_nop 0
	v_cndmask_b32_e32 v37, v37, v39, vcc
	v_rsq_f32_e32 v37, v37
	s_nop 0
	v_mul_f32_e32 v39, 0x45800000, v37
	v_cndmask_b32_e32 v66, v37, v39, vcc
	v_mul_f32_e32 v12, v12, v66
	v_mul_f32_e32 v8, v8, v66
	v_mul_f32_e32 v4, v4, v66
	v_mul_f32_e32 v0, v0, v66
	s_waitcnt vmcnt(0)
	v_mul_f32_e32 v12, v58, v12
	v_add_f32_e32 v37, 1.0, v62
	v_fma_f32 v37, v37, v12, v68
	v_mul_f32_e32 v12, v13, v66
	v_mul_f32_e32 v12, v59, v12
	v_add_f32_e32 v13, 1.0, v63
	v_fma_f32 v39, v13, v12, v69
	v_mul_f32_e32 v12, v14, v66
	v_mul_f32_e32 v12, v60, v12
	v_add_f32_e32 v13, 1.0, v64
	v_fma_f32 v41, v12, v13, v70
	v_mul_f32_e32 v12, v15, v66
	v_lshlrev_b64 v[14:15], 11, v[34:35]
	v_mul_f32_e32 v12, v61, v12
	v_add_f32_e32 v13, 1.0, v65
	v_lshl_add_u64 v[42:43], v[32:33], 0, v[14:15]
	v_fmac_f32_e32 v71, v12, v13
	v_cvt_pk_bf16_f32 v12, v37, v39
	v_cvt_pk_bf16_f32 v13, v41, v71
	global_store_dwordx2 v[42:43], v[12:13], off
	ds_read_b128 v[12:15], v53
	ds_read_b128 v[72:75], v53 offset:16
	ds_read_b128 v[76:79], v53 offset:32
	ds_read_b128 v[80:83], v53 offset:48
	s_waitcnt lgkmcnt(0)
	v_fma_f32 v65, v37, v12, 0
	v_fma_f32 v64, v37, v13, 0
	v_fma_f32 v63, v37, v14, 0
	v_fma_f32 v62, v37, v15, 0
	v_fma_f32 v61, v37, v72, 0
	v_fma_f32 v60, v37, v73, 0
	v_fma_f32 v59, v37, v74, 0
	v_fma_f32 v58, v37, v75, 0
	ds_read_b128 v[12:15], v53 offset:64
	ds_read_b128 v[72:75], v53 offset:80
	v_fmac_f32_e32 v65, v39, v76
	v_fmac_f32_e32 v64, v39, v77
	v_fmac_f32_e32 v63, v39, v78
	v_fmac_f32_e32 v62, v39, v79
	v_fmac_f32_e32 v61, v39, v80
	v_fmac_f32_e32 v60, v39, v81
	v_fmac_f32_e32 v59, v39, v82
	v_fmac_f32_e32 v58, v39, v83
	s_waitcnt lgkmcnt(0)
; __device__ __forceinline__ unsigned pack2(float a, float b) { unsigned r; asm("v_cvt_pk_bf16_f32 %0, %1, %2" : "=v"(r) : "v"(a), "v"(b)); return r; }
; __device__ __forceinline__ void route_item(const Params& p, int tile, unsigned char* smem) {
;     ...
;     for (int q = 0; q < 4; q++) {
;       int cidx = q * 256 + lane * 4;
;       float4 gg = *(const float4*)(g + cidx);
;       float4 sh = *(const float4*)(md + cidx);
;       float4 sc = *(const float4*)(md + 1024 + cidx);
;       float o[4];
;       o[0] = v[q].x * rstd * gg.x * (1.f + sc.x) + sh.x;
;       o[1] = v[q].y * rstd * gg.y * (1.f + sc.y) + sh.y;
;       o[2] = v[q].z * rstd * gg.z * (1.f + sc.z) + sh.z;
;       o[3] = v[q].w * rstd * gg.w * (1.f + sc.w) + sh.w;
;       uint2 ob; ob.x = pack2(o[0], o[1]); ob.y = pack2(o[2], o[3]);
;       *(uint2*)(XN + (size_t)row * D + cidx) = ob;
; #pragma unroll
;       for (int u = 0; u < 4; u++) {
;         float4 r0 = *(const float4*)(rw + (cidx + u) * 8);
;         float4 r1 = *(const float4*)(rw + (cidx + u) * 8 + 4);
;         lg[0] += o[u] * r0.x; lg[1] += o[u] * r0.y; lg[2] += o[u] * r0.z; lg[3] += o[u] * r0.w;
	v_fmac_f32_e32 v65, v41, v12
	v_fmac_f32_e32 v64, v41, v13
	v_fmac_f32_e32 v63, v41, v14
	v_fmac_f32_e32 v62, v41, v15
	v_fmac_f32_e32 v61, v41, v72
	v_fmac_f32_e32 v60, v41, v73
	v_fmac_f32_e32 v59, v41, v74
	v_fmac_f32_e32 v58, v41, v75
	ds_read_b128 v[12:15], v53 offset:96
	ds_read_b128 v[72:75], v53 offset:112
	v_mov_b32_e32 v37, v161
	v_lshl_add_u64 v[68:69], v[44:45], 0, v[36:37]
	s_waitcnt lgkmcnt(0)
	v_fmac_f32_e32 v65, v71, v12
	v_fmac_f32_e32 v61, v71, v72
	v_fmac_f32_e32 v60, v71, v73
	v_lshl_add_u64 v[72:73], v[46:47], 0, v[36:37]
	v_fmac_f32_e32 v64, v71, v13
	v_fmac_f32_e32 v63, v71, v14
	v_fmac_f32_e32 v62, v71, v15
	v_fmac_f32_e32 v59, v71, v74
	v_fmac_f32_e32 v58, v71, v75
	v_mov_b32_e32 v12, v84
	v_mov_b32_e32 v13, v85
	v_mov_b32_e32 v14, v86
	v_mov_b32_e32 v15, v87
	s_waitcnt lgkmcnt(0)
	v_mul_f32_e32 v8, v8, v12
	v_mov_b32_e32 v68, v88
	v_mov_b32_e32 v69, v89
	v_mov_b32_e32 v70, v90
	v_mov_b32_e32 v71, v91
	s_nop 0
	v_mov_b32_e32 v72, v92
	v_mov_b32_e32 v73, v93
	v_mov_b32_e32 v74, v94
	v_mov_b32_e32 v75, v95
	s_waitcnt lgkmcnt(0)
	v_add_f32_e32 v12, 1.0, v72
	v_fma_f32 v37, v8, v12, v68
	v_mul_f32_e32 v8, v9, v66
	v_mul_f32_e32 v8, v8, v13
	v_add_f32_e32 v9, 1.0, v73
	v_fma_f32 v39, v8, v9, v69
	v_mul_f32_e32 v8, v10, v66
	v_mul_f32_e32 v8, v8, v14
	v_add_f32_e32 v9, 1.0, v74
	v_fma_f32 v41, v8, v9, v70
	v_mul_f32_e32 v8, v11, v66
	v_mul_f32_e32 v8, v8, v15
	v_add_f32_e32 v9, 1.0, v75
	v_fmac_f32_e32 v71, v8, v9
	v_cvt_pk_bf16_f32 v8, v37, v39
	v_cvt_pk_bf16_f32 v9, v41, v71
	global_store_dwordx2 v[42:43], v[8:9], off offset:512
	ds_read_b128 v[8:11], v55
	ds_read_b128 v[12:15], v55 offset:16
	s_waitcnt lgkmcnt(0)
	v_fmac_f32_e32 v65, v37, v8
	v_fmac_f32_e32 v64, v37, v9
	v_fmac_f32_e32 v63, v37, v10
	v_fmac_f32_e32 v62, v37, v11
	v_fmac_f32_e32 v61, v37, v12
	v_fmac_f32_e32 v60, v37, v13
	v_fmac_f32_e32 v59, v37, v14
	v_fmac_f32_e32 v58, v37, v15
	ds_read_b128 v[8:11], v53 offset:8224
	ds_read_b128 v[12:15], v53 offset:8240
	ds_read_b128 v[72:75], v53 offset:8256
	ds_read_b128 v[76:79], v53 offset:8272
	s_waitcnt lgkmcnt(0)
	v_fmac_f32_e32 v65, v39, v8
	v_fmac_f32_e32 v64, v39, v9
	v_fmac_f32_e32 v63, v39, v10
	v_fmac_f32_e32 v62, v39, v11
	v_fmac_f32_e32 v61, v39, v12
	v_fmac_f32_e32 v60, v39, v13
	v_fmac_f32_e32 v59, v39, v14
	v_fmac_f32_e32 v58, v39, v15
	ds_read_b128 v[8:11], v53 offset:8288
	ds_read_b128 v[12:15], v53 offset:8304
	v_mov_b32_e32 v39, v161
	v_fmac_f32_e32 v65, v41, v72
	v_fmac_f32_e32 v64, v41, v73
	v_fmac_f32_e32 v63, v41, v74
	v_fmac_f32_e32 v62, v41, v75
	v_fmac_f32_e32 v61, v41, v76
	v_fmac_f32_e32 v60, v41, v77
	v_fmac_f32_e32 v59, v41, v78
	v_fmac_f32_e32 v58, v41, v79
	v_lshl_add_u64 v[68:69], v[46:47], 0, v[38:39]
	s_waitcnt lgkmcnt(0)
	v_fmac_f32_e32 v65, v71, v8
	v_fmac_f32_e32 v64, v71, v9
	v_fmac_f32_e32 v63, v71, v10
	v_fmac_f32_e32 v62, v71, v11
	v_fmac_f32_e32 v61, v71, v12
	v_fmac_f32_e32 v60, v71, v13
	v_fmac_f32_e32 v59, v71, v14
	v_fmac_f32_e32 v58, v71, v15
	v_mov_b32_e32 v8, v96
	v_mov_b32_e32 v9, v97
	v_mov_b32_e32 v10, v98
	v_mov_b32_e32 v11, v99
	v_lshl_add_u64 v[12:13], v[44:45], 0, v[38:39]
	v_mov_b32_e32 v68, v100
	v_mov_b32_e32 v69, v101
	v_mov_b32_e32 v70, v102
	v_mov_b32_e32 v71, v103
	v_mov_b32_e32 v41, v161
	v_mov_b32_e32 v12, v104
	v_mov_b32_e32 v13, v105
	v_mov_b32_e32 v14, v106
	v_mov_b32_e32 v15, v107
	s_waitcnt lgkmcnt(0)
	v_mul_f32_e32 v4, v4, v8
	v_add_f32_e32 v8, 1.0, v68
	v_fma_f32 v12, v4, v8, v12
	v_mul_f32_e32 v4, v5, v66
	v_mul_f32_e32 v4, v4, v9
	v_add_f32_e32 v5, 1.0, v69
	v_fma_f32 v13, v4, v5, v13
	v_mul_f32_e32 v4, v6, v66
	v_mul_f32_e32 v4, v4, v10
	v_add_f32_e32 v5, 1.0, v70
	v_fma_f32 v14, v4, v5, v14
	v_mul_f32_e32 v4, v7, v66
	v_mul_f32_e32 v4, v4, v11
	v_add_f32_e32 v5, 1.0, v71
	v_fmac_f32_e32 v15, v4, v5
	v_cvt_pk_bf16_f32 v4, v12, v13
	v_cvt_pk_bf16_f32 v5, v14, v15
	global_store_dwordx2 v[42:43], v[4:5], off offset:1024
	ds_read_b128 v[4:7], v56
	ds_read_b128 v[8:11], v56 offset:16
	s_waitcnt lgkmcnt(0)
	v_fmac_f32_e32 v65, v12, v4
	v_fmac_f32_e32 v64, v12, v5
	v_fmac_f32_e32 v63, v12, v6
	v_fmac_f32_e32 v62, v12, v7
	v_fmac_f32_e32 v61, v12, v8
	v_fmac_f32_e32 v60, v12, v9
	v_fmac_f32_e32 v59, v12, v10
	v_fmac_f32_e32 v58, v12, v11
	ds_read_b128 v[4:7], v53 offset:16416
	ds_read_b128 v[8:11], v53 offset:16432
	ds_read_b128 v[68:71], v53 offset:16448
	ds_read_b128 v[72:75], v53 offset:16464
	s_waitcnt lgkmcnt(0)
	v_fmac_f32_e32 v65, v13, v4
	v_fmac_f32_e32 v64, v13, v5
	v_fmac_f32_e32 v63, v13, v6
	v_fmac_f32_e32 v62, v13, v7
	v_fmac_f32_e32 v61, v13, v8
	v_fmac_f32_e32 v60, v13, v9
	v_fmac_f32_e32 v59, v13, v10
	v_fmac_f32_e32 v58, v13, v11
	ds_read_b128 v[4:7], v53 offset:16480
	ds_read_b128 v[8:11], v53 offset:16496
	v_fmac_f32_e32 v61, v14, v72
	v_fmac_f32_e32 v60, v14, v73
	v_fmac_f32_e32 v65, v14, v68
	v_fmac_f32_e32 v64, v14, v69
	v_fmac_f32_e32 v63, v14, v70
	v_fmac_f32_e32 v62, v14, v71
	v_fmac_f32_e32 v59, v14, v74
	v_fmac_f32_e32 v58, v14, v75
	s_waitcnt lgkmcnt(0)
	v_fmac_f32_e32 v61, v15, v8
	v_fmac_f32_e32 v60, v15, v9
	v_lshl_add_u64 v[8:9], v[44:45], 0, v[40:41]
	v_lshl_add_u64 v[12:13], v[46:47], 0, v[40:41]
	v_fmac_f32_e32 v65, v15, v4
	v_fmac_f32_e32 v64, v15, v5
	v_fmac_f32_e32 v63, v15, v6
	v_fmac_f32_e32 v62, v15, v7
	v_fmac_f32_e32 v59, v15, v10
	v_fmac_f32_e32 v58, v15, v11
	v_mov_b32_e32 v4, v108
	v_mov_b32_e32 v5, v109
	v_mov_b32_e32 v6, v110
	v_mov_b32_e32 v7, v111
	s_waitcnt lgkmcnt(0)
	v_mul_f32_e32 v0, v0, v4
	v_mov_b32_e32 v8, v112
	v_mov_b32_e32 v9, v113
	v_mov_b32_e32 v10, v114
	v_mov_b32_e32 v11, v115
	s_nop 0
	v_mov_b32_e32 v12, v116
	v_mov_b32_e32 v13, v117
	v_mov_b32_e32 v14, v118
	v_mov_b32_e32 v15, v119
	s_waitcnt lgkmcnt(0)
; __device__ __forceinline__ unsigned pack2(float a, float b) { unsigned r; asm("v_cvt_pk_bf16_f32 %0, %1, %2" : "=v"(r) : "v"(a), "v"(b)); return r; }
; __device__ __forceinline__ void route_item(const Params& p, int tile, unsigned char* smem) {
;     ...
;       o[0] = v[q].x * rstd * gg.x * (1.f + sc.x) + sh.x;
;       o[1] = v[q].y * rstd * gg.y * (1.f + sc.y) + sh.y;
;       o[2] = v[q].z * rstd * gg.z * (1.f + sc.z) + sh.z;
;       o[3] = v[q].w * rstd * gg.w * (1.f + sc.w) + sh.w;
;       uint2 ob; ob.x = pack2(o[0], o[1]); ob.y = pack2(o[2], o[3]);
;       *(uint2*)(XN + (size_t)row * D + cidx) = ob;
; #pragma unroll
;       for (int u = 0; u < 4; u++) {
;         float4 r0 = *(const float4*)(rw + (cidx + u) * 8);
;         float4 r1 = *(const float4*)(rw + (cidx + u) * 8 + 4);
;         lg[0] += o[u] * r0.x; lg[1] += o[u] * r0.y; lg[2] += o[u] * r0.z; lg[3] += o[u] * r0.w;
;         lg[4] += o[u] * r1.x; lg[5] += o[u] * r1.y; lg[6] += o[u] * r1.z; lg[7] += o[u] * r1.w;
;       }
;     }
; #pragma unroll
;     for (int e = 0; e < 8; e++) lg[e] = wave_sum(lg[e]);
	v_add_f32_e32 v4, 1.0, v12
	v_fma_f32 v4, v0, v4, v8
	v_mul_f32_e32 v0, v1, v66
	v_mul_f32_e32 v0, v0, v5
	v_add_f32_e32 v1, 1.0, v13
	v_fma_f32 v0, v0, v1, v9
	v_mul_f32_e32 v1, v2, v66
	v_mul_f32_e32 v1, v1, v6
	v_add_f32_e32 v2, 1.0, v14
	v_fma_f32 v1, v1, v2, v10
	v_mul_f32_e32 v2, v3, v66
	v_mul_f32_e32 v2, v2, v7
	v_add_f32_e32 v3, 1.0, v15
	v_fmac_f32_e32 v11, v2, v3
	v_cvt_pk_bf16_f32 v2, v4, v0
	v_cvt_pk_bf16_f32 v3, v1, v11
	global_store_dwordx2 v[42:43], v[2:3], off offset:1536
	ds_read_b128 v[6:9], v57
	ds_read_b128 v[12:15], v57 offset:16
	s_waitcnt lgkmcnt(0)
	v_fmac_f32_e32 v65, v4, v6
	v_fmac_f32_e32 v64, v4, v7
	v_fmac_f32_e32 v63, v4, v8
	v_fmac_f32_e32 v62, v4, v9
	v_fmac_f32_e32 v61, v4, v12
	v_fmac_f32_e32 v60, v4, v13
	v_fmac_f32_e32 v59, v4, v14
	v_fmac_f32_e32 v58, v4, v15
	ds_read_b128 v[2:5], v53 offset:24608
	ds_read_b128 v[6:9], v53 offset:24624
	ds_read_b128 v[12:15], v53 offset:24640
	ds_read_b128 v[42:45], v53 offset:24656
	s_waitcnt lgkmcnt(0)
	v_fmac_f32_e32 v65, v0, v2
	v_fmac_f32_e32 v64, v0, v3
	v_fmac_f32_e32 v63, v0, v4
	v_fmac_f32_e32 v62, v0, v5
	v_fmac_f32_e32 v61, v0, v6
	v_fmac_f32_e32 v60, v0, v7
	v_fmac_f32_e32 v59, v0, v8
	v_fmac_f32_e32 v58, v0, v9
	v_fmac_f32_e32 v65, v1, v12
	v_fmac_f32_e32 v64, v1, v13
	v_fmac_f32_e32 v63, v1, v14
	v_fmac_f32_e32 v62, v1, v15
	v_fmac_f32_e32 v61, v1, v42
	v_fmac_f32_e32 v60, v1, v43
	v_fmac_f32_e32 v59, v1, v44
	v_fmac_f32_e32 v58, v1, v45
	ds_read_b128 v[0:3], v53 offset:24672
	ds_read_b128 v[4:7], v53 offset:24688
	s_waitcnt lgkmcnt(0)
	v_fmac_f32_e32 v65, v11, v0
	v_fmac_f32_e32 v64, v11, v1
	v_fmac_f32_e32 v63, v11, v2
	v_fmac_f32_e32 v62, v11, v3
	v_fmac_f32_e32 v61, v11, v4
	v_fmac_f32_e32 v60, v11, v5
	v_fmac_f32_e32 v59, v11, v6
	v_fmac_f32_e32 v58, v11, v7
	ds_bpermute_b32 v0, v17, v65
	ds_bpermute_b32 v2, v17, v64
	ds_bpermute_b32 v4, v17, v63
	ds_bpermute_b32 v6, v17, v62
	ds_bpermute_b32 v8, v17, v61
	ds_bpermute_b32 v10, v17, v60
	ds_bpermute_b32 v12, v17, v59
	ds_bpermute_b32 v14, v17, v58
	s_waitcnt lgkmcnt(0)
	v_add_f32_e32 v0, v65, v0
	v_add_f32_e32 v2, v64, v2
	v_add_f32_e32 v4, v63, v4
	v_add_f32_e32 v6, v62, v6
	v_add_f32_e32 v8, v61, v8
	v_add_f32_e32 v10, v60, v10
	v_add_f32_e32 v12, v59, v12
	v_add_f32_e32 v14, v58, v14
	ds_bpermute_b32 v1, v48, v0
	ds_bpermute_b32 v3, v48, v2
	ds_bpermute_b32 v5, v48, v4
	ds_bpermute_b32 v7, v48, v6
	ds_bpermute_b32 v9, v48, v8
	ds_bpermute_b32 v11, v48, v10
	ds_bpermute_b32 v13, v48, v12
	ds_bpermute_b32 v15, v48, v14
	s_waitcnt lgkmcnt(0)
	v_add_f32_e32 v0, v0, v1
	v_add_f32_e32 v2, v2, v3
	v_add_f32_e32 v4, v4, v5
	v_add_f32_e32 v6, v6, v7
	v_add_f32_e32 v8, v8, v9
	v_add_f32_e32 v10, v10, v11
	v_add_f32_e32 v12, v12, v13
	v_add_f32_e32 v14, v14, v15
	ds_bpermute_b32 v1, v49, v0
	ds_bpermute_b32 v3, v49, v2
	ds_bpermute_b32 v5, v49, v4
	ds_bpermute_b32 v7, v49, v6
	ds_bpermute_b32 v9, v49, v8
	ds_bpermute_b32 v11, v49, v10
	ds_bpermute_b32 v13, v49, v12
	ds_bpermute_b32 v15, v49, v14
	s_waitcnt lgkmcnt(0)
	v_add_f32_e32 v0, v0, v1
	v_add_f32_e32 v2, v2, v3
	v_add_f32_e32 v4, v4, v5
	v_add_f32_e32 v6, v6, v7
	v_add_f32_e32 v8, v8, v9
	v_add_f32_e32 v10, v10, v11
	v_add_f32_e32 v12, v12, v13
	v_add_f32_e32 v14, v14, v15
	ds_bpermute_b32 v1, v50, v0
	ds_bpermute_b32 v3, v50, v2
	ds_bpermute_b32 v5, v50, v4
	ds_bpermute_b32 v7, v50, v6
	ds_bpermute_b32 v9, v50, v8
	ds_bpermute_b32 v11, v50, v10
	ds_bpermute_b32 v13, v50, v12
	ds_bpermute_b32 v15, v50, v14
	s_waitcnt lgkmcnt(0)
	v_add_f32_e32 v0, v0, v1
	v_add_f32_e32 v2, v2, v3
	v_add_f32_e32 v4, v4, v5
	v_add_f32_e32 v6, v6, v7
	v_add_f32_e32 v8, v8, v9
	v_add_f32_e32 v10, v10, v11
	v_add_f32_e32 v12, v12, v13
	v_add_f32_e32 v14, v14, v15
	ds_bpermute_b32 v1, v51, v0
	ds_bpermute_b32 v3, v51, v2
	ds_bpermute_b32 v5, v51, v4
	ds_bpermute_b32 v7, v51, v6
	ds_bpermute_b32 v9, v51, v8
	ds_bpermute_b32 v11, v51, v10
	ds_bpermute_b32 v13, v51, v12
	ds_bpermute_b32 v15, v51, v14
	s_waitcnt lgkmcnt(0)
	v_add_f32_e32 v0, v0, v1
	v_add_f32_e32 v2, v2, v3
	v_add_f32_e32 v4, v4, v5
	v_add_f32_e32 v6, v6, v7
	v_add_f32_e32 v8, v8, v9
	v_add_f32_e32 v10, v10, v11
	v_add_f32_e32 v12, v12, v13
	v_add_f32_e32 v14, v14, v15
	ds_bpermute_b32 v1, v52, v0
	ds_bpermute_b32 v3, v52, v2
	ds_bpermute_b32 v5, v52, v4
	ds_bpermute_b32 v7, v52, v6
	ds_bpermute_b32 v9, v52, v8
	ds_bpermute_b32 v11, v52, v10
	ds_bpermute_b32 v13, v52, v12
	ds_bpermute_b32 v15, v52, v14
	s_and_saveexec_b64 s[26:27], s[8:9]
	s_cbranch_execz .LBB0_1005
; __device__ __forceinline__ void route_item(const Params& p, int tile, unsigned char* smem) {
;     ...
;     for (int e = 0; e < 8; e++) lg[e] = wave_sum(lg[e]);
;     float mx = lg[0];
; #pragma unroll
;     for (int e = 1; e < 8; e++) mx = fmaxf(mx, lg[e]);
;     float pr[8];
; #pragma unroll
;     for (int e = 0; e < 8; e++) pr[e] = expf(lg[e] - mx);
;     int e0 = 0; float p0 = pr[0];
; #pragma unroll
;     for (int e = 1; e < 8; e++) if (pr[e] > p0) { p0 = pr[e]; e0 = e; }
;     int e1 = -1; float p1 = -1.f;
; #pragma unroll
;     for (int e = 0; e < 8; e++) if (e != e0 && pr[e] > p1) { p1 = pr[e]; e1 = e; }
;     float inv = 1.0f / (p0 + p1);
;     if (lane == 0) {
;       TOKE[row] = make_int2(e0, e1);
;       TOKW[row] = make_float2(p0 * inv, p1 * inv);
;       te[rl * 2] = e0; te[rl * 2 + 1] = e1;
	s_waitcnt lgkmcnt(0)
	v_add_f32_e32 v0, v0, v1
	v_add_f32_e32 v1, v2, v3
	v_max_f32_e32 v2, v0, v1
	v_add_f32_e32 v3, v4, v5
	v_add_f32_e32 v4, v6, v7
	v_max3_f32 v2, v2, v3, v4
	v_add_f32_e32 v5, v8, v9
	v_add_f32_e32 v6, v10, v11
	v_add_f32_e32 v14, v14, v15
	v_max3_f32 v2, v2, v5, v6
	v_add_f32_e32 v7, v12, v13
	v_max3_f32 v2, v2, v7, v14
	v_sub_f32_e32 v8, v14, v2
	v_mul_f32_e32 v9, 0x3fb8aa3b, v8
	v_fma_f32 v10, v8, s55, -v9
	v_rndne_f32_e32 v11, v9
	v_fmac_f32_e32 v10, 0x32a5705f, v8
	v_sub_f32_e32 v9, v9, v11
	v_add_f32_e32 v9, v9, v10
	v_exp_f32_e32 v9, v9
	v_cvt_i32_f32_e32 v10, v11
	v_sub_f32_e32 v7, v7, v2
	v_cmp_ngt_f32_e32 vcc, s56, v8
	v_sub_f32_e32 v6, v6, v2
	v_ldexp_f32 v9, v9, v10
	v_mul_f32_e32 v10, 0x3fb8aa3b, v7
	v_fma_f32 v11, v7, s55, -v10
	v_rndne_f32_e32 v12, v10
	v_fmac_f32_e32 v11, 0x32a5705f, v7
	v_sub_f32_e32 v10, v10, v12
	v_add_f32_e32 v10, v10, v11
	v_exp_f32_e32 v10, v10
	v_cvt_i32_f32_e32 v11, v12
	v_cndmask_b32_e32 v9, 0, v9, vcc
	v_cmp_nlt_f32_e32 vcc, s54, v8
	v_sub_f32_e32 v5, v5, v2
	v_sub_f32_e32 v4, v4, v2
	v_cndmask_b32_e32 v8, v242, v9, vcc
	v_ldexp_f32 v9, v10, v11
	v_mul_f32_e32 v10, 0x3fb8aa3b, v6
	v_fma_f32 v11, v6, s55, -v10
	v_rndne_f32_e32 v12, v10
	v_fmac_f32_e32 v11, 0x32a5705f, v6
	v_sub_f32_e32 v10, v10, v12
	v_add_f32_e32 v10, v10, v11
	v_exp_f32_e32 v10, v10
	v_cvt_i32_f32_e32 v11, v12
	v_cmp_ngt_f32_e32 vcc, s56, v7
	v_sub_f32_e32 v3, v3, v2
	v_sub_f32_e32 v1, v1, v2
	v_cndmask_b32_e32 v9, 0, v9, vcc
	v_cmp_nlt_f32_e32 vcc, s54, v7
	v_sub_f32_e32 v0, v0, v2
	v_mul_f32_e32 v2, 0x3fb8aa3b, v0
	v_cndmask_b32_e32 v7, v242, v9, vcc
	v_ldexp_f32 v9, v10, v11
	v_mul_f32_e32 v10, 0x3fb8aa3b, v5
	v_fma_f32 v11, v5, s55, -v10
	v_rndne_f32_e32 v12, v10
	v_fmac_f32_e32 v11, 0x32a5705f, v5
	v_sub_f32_e32 v10, v10, v12
	v_add_f32_e32 v10, v10, v11
	v_exp_f32_e32 v10, v10
	v_cvt_i32_f32_e32 v11, v12
	v_cmp_ngt_f32_e32 vcc, s56, v6
	s_nop 1
	v_cndmask_b32_e32 v9, 0, v9, vcc
	v_cmp_nlt_f32_e32 vcc, s54, v6
	s_nop 1
	v_cndmask_b32_e32 v6, v242, v9, vcc
	v_ldexp_f32 v9, v10, v11
	v_mul_f32_e32 v10, 0x3fb8aa3b, v4
	v_fma_f32 v11, v4, s55, -v10
	v_rndne_f32_e32 v12, v10
	v_fmac_f32_e32 v11, 0x32a5705f, v4
	v_sub_f32_e32 v10, v10, v12
	v_add_f32_e32 v10, v10, v11
	v_exp_f32_e32 v10, v10
	v_cvt_i32_f32_e32 v11, v12
	v_cmp_ngt_f32_e32 vcc, s56, v5
	s_nop 1
	v_cndmask_b32_e32 v9, 0, v9, vcc
	v_cmp_nlt_f32_e32 vcc, s54, v5
	s_nop 1
	v_cndmask_b32_e32 v5, v242, v9, vcc
	v_ldexp_f32 v9, v10, v11
	v_mul_f32_e32 v10, 0x3fb8aa3b, v3
	v_fma_f32 v11, v3, s55, -v10
	v_rndne_f32_e32 v12, v10
	v_fmac_f32_e32 v11, 0x32a5705f, v3
	v_sub_f32_e32 v10, v10, v12
	v_add_f32_e32 v10, v10, v11
	v_exp_f32_e32 v10, v10
	v_cvt_i32_f32_e32 v11, v12
	v_cmp_ngt_f32_e32 vcc, s56, v4
	s_nop 1
	v_cndmask_b32_e32 v9, 0, v9, vcc
	v_cmp_nlt_f32_e32 vcc, s54, v4
	s_nop 1
	v_cndmask_b32_e32 v4, v242, v9, vcc
	v_ldexp_f32 v9, v10, v11
	v_mul_f32_e32 v10, 0x3fb8aa3b, v1
	v_fma_f32 v11, v1, s55, -v10
	v_rndne_f32_e32 v12, v10
	v_fmac_f32_e32 v11, 0x32a5705f, v1
	v_sub_f32_e32 v10, v10, v12
	v_add_f32_e32 v10, v10, v11
	v_exp_f32_e32 v10, v10
	v_cvt_i32_f32_e32 v11, v12
	v_cmp_ngt_f32_e32 vcc, s56, v3
	s_nop 1
	v_cndmask_b32_e32 v9, 0, v9, vcc
	v_cmp_nlt_f32_e32 vcc, s54, v3
	s_nop 1
	v_cndmask_b32_e32 v3, v242, v9, vcc
	v_ldexp_f32 v9, v10, v11
	v_fma_f32 v10, v0, s55, -v2
	v_rndne_f32_e32 v11, v2
	v_fmac_f32_e32 v10, 0x32a5705f, v0
	v_sub_f32_e32 v2, v2, v11
	v_add_f32_e32 v2, v2, v10
	v_exp_f32_e32 v2, v2
	v_cvt_i32_f32_e32 v10, v11
	v_cmp_ngt_f32_e32 vcc, s56, v1
	v_ldexp_f32 v2, v2, v10
	s_nop 0
	v_cndmask_b32_e32 v9, 0, v9, vcc
	v_cmp_nlt_f32_e32 vcc, s54, v1
	s_nop 1
	v_cndmask_b32_e32 v1, v242, v9, vcc
	v_cmp_ngt_f32_e32 vcc, s56, v0
	s_nop 1
	v_cndmask_b32_e32 v2, 0, v2, vcc
	v_cmp_nlt_f32_e32 vcc, s54, v0
	s_nop 1
	v_cndmask_b32_e32 v2, v242, v2, vcc
	v_cmp_gt_f32_e32 vcc, v1, v2
	v_cmp_nlt_f32_e64 s[22:23], -1.0, v2
	s_nop 0
	v_cndmask_b32_e32 v0, v2, v1, vcc
	v_cmp_gt_f32_e64 s[10:11], v3, v0
	s_nop 1
	v_cndmask_b32_e64 v0, v0, v3, s[10:11]
	v_cmp_gt_f32_e64 s[12:13], v4, v0
	s_nop 1
	v_cndmask_b32_e64 v0, v0, v4, s[12:13]
	v_cmp_gt_f32_e64 s[14:15], v5, v0
	s_nop 1
	v_cndmask_b32_e64 v0, v0, v5, s[14:15]
	v_cmp_gt_f32_e64 s[16:17], v6, v0
	s_nop 1
	v_cndmask_b32_e64 v0, v0, v6, s[16:17]
	v_cmp_gt_f32_e64 s[18:19], v7, v0
	s_nop 1
	v_cndmask_b32_e64 v9, v0, v7, s[18:19]
	v_cndmask_b32_e64 v0, 0, 1, vcc
	v_cndmask_b32_e64 v0, v0, 2, s[10:11]
	v_cndmask_b32_e64 v0, v0, 3, s[12:13]
	v_cndmask_b32_e64 v0, v0, 4, s[14:15]
	v_cndmask_b32_e64 v0, v0, 5, s[16:17]
	v_cndmask_b32_e64 v0, v0, 6, s[18:19]
	v_cmp_ngt_f32_e32 vcc, v8, v9
	s_and_b64 s[30:31], s[18:19], vcc
	s_nop 0
	v_cndmask_b32_e32 v0, 7, v0, vcc
	v_cmp_eq_u32_e64 s[20:21], 0, v0
	s_or_b64 s[34:35], s[22:23], s[20:21]
	v_cndmask_b32_e64 v2, v2, -1.0, s[34:35]
	v_cmp_ne_u32_e64 s[18:19], 1, v0
	v_cmp_gt_f32_e64 s[20:21], v1, v2
	s_and_b64 s[18:19], s[18:19], s[20:21]
	v_cndmask_b32_e64 v1, v2, v1, s[18:19]
	v_cmp_ne_u32_e64 s[16:17], 2, v0
	v_cmp_gt_f32_e64 s[20:21], v3, v1
	s_and_b64 s[16:17], s[16:17], s[20:21]
	v_cndmask_b32_e64 v1, v1, v3, s[16:17]
	v_cmp_ne_u32_e64 s[14:15], 3, v0
	v_cmp_gt_f32_e64 s[20:21], v4, v1
	s_and_b64 s[14:15], s[14:15], s[20:21]
	v_cndmask_b32_e64 v1, v1, v4, s[14:15]
	v_cmp_ne_u32_e64 s[12:13], 4, v0
	v_cmp_gt_f32_e64 s[20:21], v5, v1
	s_and_b64 s[12:13], s[12:13], s[20:21]
	v_cndmask_b32_e64 v1, v1, v5, s[12:13]
	v_cmp_ne_u32_e64 s[10:11], 5, v0
	v_cmp_gt_f32_e64 s[20:21], v6, v1
	s_and_b64 s[10:11], s[10:11], s[20:21]
	v_cndmask_b32_e64 v1, v1, v6, s[10:11]
	v_cmp_ngt_f32_e64 s[20:21], v7, v1
	s_or_b64 s[20:21], s[30:31], s[20:21]
	s_nop 0
	v_cndmask_b32_e64 v1, v7, v1, s[20:21]
	v_cmp_gt_f32_e64 s[22:23], v8, v1
	s_and_b64 s[22:23], vcc, s[22:23]
	v_cndmask_b32_e32 v7, v8, v9, vcc
	v_cndmask_b32_e64 v6, v1, v8, s[22:23]
	v_cndmask_b32_e64 v1, 0, -1, s[34:35]
	v_cndmask_b32_e64 v1, v1, 1, s[18:19]
	v_cndmask_b32_e64 v1, v1, 2, s[16:17]
	v_cndmask_b32_e64 v1, v1, 3, s[14:15]
	v_add_f32_e32 v2, v7, v6
	v_cndmask_b32_e64 v1, v1, 4, s[12:13]
	v_div_scale_f32 v3, s[12:13], v2, v2, 1.0
	v_rcp_f32_e32 v4, v3
	v_cndmask_b32_e64 v1, v1, 5, s[10:11]
	v_cndmask_b32_e64 v1, 6, v1, s[20:21]
	v_cndmask_b32_e64 v1, v1, 7, s[22:23]
	v_fma_f32 v5, -v3, v4, 1.0
	v_fmac_f32_e32 v4, v5, v4
	v_div_scale_f32 v5, vcc, 1.0, v2, 1.0
	v_mul_f32_e32 v8, v5, v4
	v_fma_f32 v9, -v3, v8, v5
	v_fmac_f32_e32 v8, v9, v4
	v_fma_f32 v3, -v3, v8, v5
	v_div_fmas_f32 v3, v3, v4, v8
	v_div_fixup_f32 v8, v3, v2, 1.0
	v_lshlrev_b64 v[2:3], 3, v[34:35]
	v_lshl_add_u64 v[4:5], v[20:21], 0, v[2:3]
	global_store_dwordx2 v[4:5], v[0:1], off
	v_mul_f32_e32 v4, v7, v8
	v_mul_f32_e32 v5, v6, v8
	v_lshl_add_u64 v[2:3], v[22:23], 0, v[2:3]
	global_store_dwordx2 v[2:3], v[4:5], off
	v_add_u32_e32 v2, s28, v54
	ds_write_b64 v2, v[0:1]
	s_branch .LBB0_1005
